# diff loops unrolled by two with static LDS ring offsets (no per-iteration address toggles)
# baseline (speedup 1.0000x reference)
.Lnoprio_925:
	v_add_u32_e32 v248, 0x8000, v248
	v_add_u32_e32 v245, 0x8000, v245
	v_lshlrev_b32_e32 v136, 1, v160
	s_barrier
	s_branch .LBB0_926
.LBB0_925:
	s_waitcnt lgkmcnt(1)
	v_mfma_f32_16x16x32_bf16 v[172:175], v[130:133], v[34:37], v[2:5]
	ds_read_b128 v[184:187], v247 offset:2048
	v_mfma_f32_16x16x32_bf16 v[180:183], v[130:133], v[38:41], v[10:13]
	ds_read_b128 v[130:133], v247
	s_nop 2
	s_nop 1
	v_exp_f32_e32 v200, v172
	v_exp_f32_e32 v201, v175
	s_waitcnt lgkmcnt(2)
	v_mfma_f32_16x16x32_bf16 v[176:179], v[168:171], v[34:37], v[2:5]
	v_exp_f32_e32 v180, v180
	ds_read_b64 v[216:217], v248 offset:4608
	ds_read_b64 v[218:219], v248 offset:4640
	v_mfma_f32_16x16x32_bf16 v[168:171], v[168:171], v[38:41], v[10:13]
	ds_read_b64 v[220:221], v248 offset:6912
	ds_read_b64 v[222:223], v248 offset:6944
	s_nop 2
	v_exp_f32_e32 v204, v176
	v_exp_f32_e32 v176, v173
	s_waitcnt lgkmcnt(4)
	v_mfma_f32_16x16x32_bf16 v[188:191], v[130:133], v[42:45], v[6:9]
	v_exp_f32_e32 v205, v177
	v_exp_f32_e32 v213, v168
	v_exp_f32_e32 v168, v181
	v_mfma_f32_16x16x32_bf16 v[196:199], v[130:133], v[46:49], v[14:17]
	ds_read_b128 v[130:133], v246 offset:4096
	v_exp_f32_e32 v181, v169
	v_exp_f32_e32 v169, v182
	v_exp_f32_e32 v182, v170
	v_exp_f32_e32 v170, v183
	v_exp_f32_e32 v171, v171
	v_exp_f32_e32 v177, v174
	v_cvt_pk_bf16_f32 v168, v180, v168
	v_cvt_pk_bf16_f32 v169, v169, v170
	v_cvt_pk_bf16_f32 v170, v213, v181
	v_cvt_pk_bf16_f32 v171, v182, v171
	ds_read_b64 v[180:181], v248 offset:0
	ds_read_b64 v[182:183], v248 offset:32
	ds_read_b64 v[212:213], v248 offset:2304
	ds_read_b64 v[214:215], v248 offset:2336
	ds_read_b128 v[172:175], v246 offset:6144
	v_cvt_pk_bf16_f32 v176, v200, v176
	v_cvt_pk_bf16_f32 v177, v177, v201
	s_waitcnt lgkmcnt(5)
	v_mfma_f32_16x16x32_bf16 v[200:203], v[130:133], v[34:37], v[2:5]
	v_exp_f32_e32 v231, v190
	v_exp_f32_e32 v206, v178
	v_exp_f32_e32 v179, v179
	v_mfma_f32_16x16x32_bf16 v[208:211], v[130:133], v[38:41], v[10:13]
	v_exp_f32_e32 v188, v188
	v_mfma_f32_16x16x32_bf16 v[192:195], v[184:187], v[42:45], v[6:9]
	v_exp_f32_e32 v189, v189
	v_exp_f32_e32 v196, v196
	v_cvt_pk_bf16_f32 v178, v204, v205
	v_mfma_f32_16x16x32_bf16 v[184:187], v[184:187], v[46:49], v[14:17]
	v_cvt_pk_bf16_f32 v179, v206, v179
	s_nop 2
	v_exp_f32_e32 v192, v192
	v_exp_f32_e32 v193, v193
	v_mfma_f32_16x16x32_bf16 v[86:89], v[240:243], v[168:171], v[86:89]
	v_exp_f32_e32 v194, v194
	v_exp_f32_e32 v187, v187
	ds_read_b128 v[224:227], v247 offset:4096
	s_waitcnt lgkmcnt(4)
	v_mfma_f32_16x16x32_bf16 v[78:81], v[180:183], v[168:171], v[78:81]
	s_add_i32 s38, s38, 2
	s_addk_i32 s12, 0x80
	v_lshl_add_u64 v[148:149], v[148:149], 0, s[16:17]
	s_waitcnt lgkmcnt(2)
	v_mfma_f32_16x16x32_bf16 v[74:77], v[212:215], v[168:171], v[74:77]
	s_and_b64 vcc, exec, s[0:1]
	v_mfma_f32_16x16x32_bf16 v[70:73], v[216:219], v[168:171], v[70:73]
	v_mfma_f32_16x16x32_bf16 v[62:65], v[220:223], v[168:171], v[62:65]
	v_exp_f32_e32 v169, v191
	v_exp_f32_e32 v171, v195
	v_cvt_pk_bf16_f32 v168, v188, v189
	s_waitcnt lgkmcnt(1)
	v_mfma_f32_16x16x32_bf16 v[204:207], v[172:175], v[34:37], v[2:5]
	v_cvt_pk_bf16_f32 v169, v231, v169
	v_exp_f32_e32 v231, v184
	v_exp_f32_e32 v184, v197
	v_exp_f32_e32 v197, v185
	v_exp_f32_e32 v185, v198
	v_exp_f32_e32 v198, v186
	v_exp_f32_e32 v186, v199
	v_cvt_pk_bf16_f32 v170, v192, v193
	v_cvt_pk_bf16_f32 v171, v194, v171
	v_cvt_pk_bf16_f32 v184, v196, v184
	v_cvt_pk_bf16_f32 v185, v185, v186
	v_cvt_pk_bf16_f32 v186, v231, v197
	v_cvt_pk_bf16_f32 v187, v198, v187
	v_mfma_f32_16x16x32_bf16 v[172:175], v[172:175], v[38:41], v[10:13]
	v_exp_f32_e32 v196, v200
	v_exp_f32_e32 v197, v204
	v_exp_f32_e32 v198, v201
	v_mfma_f32_16x16x32_bf16 v[122:125], v[180:183], v[176:179], v[122:125]
	v_exp_f32_e32 v200, v207
	v_exp_f32_e32 v199, v203
	v_mfma_f32_16x16x32_bf16 v[102:105], v[180:183], v[168:171], v[102:105]
	v_mfma_f32_16x16x32_bf16 v[58:61], v[180:183], v[184:187], v[58:61]
	v_exp_f32_e32 v182, v205
	v_exp_f32_e32 v183, v206
	v_exp_f32_e32 v181, v202
	v_mfma_f32_16x16x32_bf16 v[126:129], v[240:243], v[176:179], v[126:129]
	v_cvt_pk_bf16_f32 v180, v196, v198
	v_cvt_pk_bf16_f32 v182, v197, v182
	v_cvt_pk_bf16_f32 v183, v183, v200
	v_mfma_f32_16x16x32_bf16 v[118:121], v[212:215], v[176:179], v[118:121]
	v_exp_f32_e32 v196, v208
	v_exp_f32_e32 v197, v172
	v_exp_f32_e32 v172, v209
	v_mfma_f32_16x16x32_bf16 v[110:113], v[216:219], v[176:179], v[110:113]
	v_exp_f32_e32 v200, v174
	v_cvt_pk_bf16_f32 v181, v181, v199
	v_exp_f32_e32 v198, v173
	v_mfma_f32_16x16x32_bf16 v[106:109], v[220:223], v[176:179], v[106:109]
	ds_read_b128 v[176:179], v247 offset:6144
	v_exp_f32_e32 v199, v210
	ds_read_b128 v[204:207], v246 offset:14336
	v_mfma_f32_16x16x32_bf16 v[114:117], v[240:243], v[168:171], v[114:117]
	v_mfma_f32_16x16x32_bf16 v[98:101], v[212:215], v[168:171], v[98:101]
	v_mfma_f32_16x16x32_bf16 v[94:97], v[216:219], v[168:171], v[94:97]
	v_mfma_f32_16x16x32_bf16 v[90:93], v[220:223], v[168:171], v[90:93]
	v_exp_f32_e32 v171, v175
	v_exp_f32_e32 v169, v211
	v_cvt_pk_bf16_f32 v168, v196, v172
	v_mfma_f32_16x16x32_bf16 v[82:85], v[240:243], v[184:187], v[82:85]
	v_cvt_pk_bf16_f32 v171, v200, v171
	v_mfma_f32_16x16x32_bf16 v[54:57], v[212:215], v[184:187], v[54:57]
	ds_read_b64 v[172:173], v248 offset:64
	ds_read_b64 v[174:175], v248 offset:96
	v_cvt_pk_bf16_f32 v169, v199, v169
	v_mfma_f32_16x16x32_bf16 v[50:53], v[216:219], v[184:187], v[50:53]
	v_cvt_pk_bf16_f32 v170, v197, v198
	ds_read_b64 v[196:197], v248 offset:4672
	ds_read_b64 v[198:199], v248 offset:4704
	ds_read_b64 v[200:201], v248 offset:6976
	ds_read_b64 v[202:203], v248 offset:7008
	v_mfma_f32_16x16x32_bf16 v[66:69], v[220:223], v[184:187], v[66:69]
	ds_read_b64 v[184:185], v248 offset:2368
	ds_read_b64 v[186:187], v248 offset:2400
	s_waitcnt lgkmcnt(10)
	v_mfma_f32_16x16x32_bf16 v[188:191], v[224:227], v[42:45], v[6:9]
	ds_read_b64 v[216:217], v248 offset:13824
	ds_read_b64 v[218:219], v248 offset:13856
	s_waitcnt lgkmcnt(11)
	v_mfma_f32_16x16x32_bf16 v[192:195], v[176:179], v[42:45], v[6:9]
	ds_read_b64 v[220:221], v248 offset:16128
	ds_read_b64 v[222:223], v248 offset:16160
	s_nop 1
	v_exp_f32_e32 v188, v188
	v_exp_f32_e32 v189, v189
	v_mfma_f32_16x16x32_bf16 v[224:227], v[224:227], v[46:49], v[14:17]
	v_exp_f32_e32 v190, v190
	s_nop 0
	v_exp_f32_e32 v192, v192
	v_exp_f32_e32 v193, v193
	v_mfma_f32_16x16x32_bf16 v[176:179], v[176:179], v[46:49], v[14:17]
	v_exp_f32_e32 v191, v191
	v_exp_f32_e32 v194, v194
	v_exp_f32_e32 v195, v195
	v_mfma_f32_16x16x32_bf16 v[126:129], v[240:243], v[180:183], v[126:129]
	v_cvt_pk_bf16_f32 v188, v188, v189
	v_cvt_pk_bf16_f32 v189, v190, v191
	v_cvt_pk_bf16_f32 v190, v192, v193
	v_mfma_f32_16x16x32_bf16 v[86:89], v[240:243], v[168:171], v[86:89]
	v_exp_f32_e32 v192, v224
	v_exp_f32_e32 v176, v176
	v_exp_f32_e32 v193, v225
	s_waitcnt lgkmcnt(10)
	v_mfma_f32_16x16x32_bf16 v[122:125], v[172:175], v[180:183], v[122:125]
	v_exp_f32_e32 v177, v177
	v_exp_f32_e32 v178, v178
	v_cvt_pk_bf16_f32 v191, v194, v195
	v_mfma_f32_16x16x32_bf16 v[78:81], v[172:175], v[168:171], v[78:81]
	s_waitcnt lgkmcnt(4)
	v_mfma_f32_16x16x32_bf16 v[118:121], v[184:187], v[180:183], v[118:121]
	v_mfma_f32_16x16x32_bf16 v[74:77], v[184:187], v[168:171], v[74:77]
	v_mfma_f32_16x16x32_bf16 v[110:113], v[196:199], v[180:183], v[110:113]
	v_mfma_f32_16x16x32_bf16 v[70:73], v[196:199], v[168:171], v[70:73]
	v_mfma_f32_16x16x32_bf16 v[106:109], v[200:203], v[180:183], v[106:109]
	v_exp_f32_e32 v180, v226
	v_mfma_f32_16x16x32_bf16 v[62:65], v[200:203], v[168:171], v[62:65]
	v_exp_f32_e32 v169, v227
	v_exp_f32_e32 v171, v179
	v_cvt_pk_bf16_f32 v168, v192, v193
	v_cvt_pk_bf16_f32 v170, v176, v177
	v_cvt_pk_bf16_f32 v169, v180, v169
	v_cvt_pk_bf16_f32 v171, v178, v171
	v_mfma_f32_16x16x32_bf16 v[102:105], v[172:175], v[188:191], v[102:105]
	ds_read_b128 v[224:227], v247 offset:12288
	v_mfma_f32_16x16x32_bf16 v[82:85], v[240:243], v[168:171], v[82:85]
	v_mfma_f32_16x16x32_bf16 v[58:61], v[172:175], v[168:171], v[58:61]
	ds_read_b128 v[172:175], v246 offset:8192
	v_mfma_f32_16x16x32_bf16 v[54:57], v[184:187], v[168:171], v[54:57]
	v_mfma_f32_16x16x32_bf16 v[50:53], v[196:199], v[168:171], v[50:53]
	v_mfma_f32_16x16x32_bf16 v[66:69], v[200:203], v[168:171], v[66:69]
	ds_read_b128 v[168:171], v246 offset:10240
	s_waitcnt lgkmcnt(1)
	v_mfma_f32_16x16x32_bf16 v[176:179], v[172:175], v[34:37], v[2:5]
	s_waitcnt lgkmcnt(0)
	v_mfma_f32_16x16x32_bf16 v[180:183], v[168:171], v[34:37], v[2:5]
	s_nop 5
	v_exp_f32_e32 v176, v176
	v_mfma_f32_16x16x32_bf16 v[172:175], v[172:175], v[38:41], v[10:13]
	v_exp_f32_e32 v208, v180
	v_exp_f32_e32 v177, v177
	v_exp_f32_e32 v209, v181
	v_mfma_f32_16x16x32_bf16 v[168:171], v[168:171], v[38:41], v[10:13]
	v_exp_f32_e32 v178, v178
	s_nop 2
	v_exp_f32_e32 v172, v172
	v_exp_f32_e32 v210, v182
	v_mfma_f32_16x16x32_bf16 v[114:117], v[240:243], v[188:191], v[114:117]
	v_exp_f32_e32 v179, v179
	v_exp_f32_e32 v213, v168
	v_exp_f32_e32 v168, v173
	v_exp_f32_e32 v173, v169
	v_exp_f32_e32 v169, v174
	v_exp_f32_e32 v174, v170
	v_exp_f32_e32 v170, v175
	v_exp_f32_e32 v171, v171
	v_mfma_f32_16x16x32_bf16 v[98:101], v[184:187], v[188:191], v[98:101]
	ds_read_b128 v[184:187], v247 offset:8192
	v_cvt_pk_bf16_f32 v168, v172, v168
	v_cvt_pk_bf16_f32 v169, v169, v170
	v_mfma_f32_16x16x32_bf16 v[94:97], v[196:199], v[188:191], v[94:97]
	v_cvt_pk_bf16_f32 v170, v213, v173
	v_cvt_pk_bf16_f32 v171, v174, v171
	ds_read_b64 v[172:173], v248 offset:9216
	ds_read_b64 v[174:175], v248 offset:9248
	v_mfma_f32_16x16x32_bf16 v[90:93], v[200:203], v[188:191], v[90:93]
	ds_read_b128 v[188:191], v247 offset:10240
	ds_read_b64 v[212:213], v248 offset:11520
	ds_read_b64 v[214:215], v248 offset:11552
	ds_read_b128 v[200:203], v246 offset:12288
	s_waitcnt lgkmcnt(6)
	v_mfma_f32_16x16x32_bf16 v[192:195], v[184:187], v[42:45], v[6:9]
	v_exp_f32_e32 v211, v183
	v_cvt_pk_bf16_f32 v176, v176, v177
	v_cvt_pk_bf16_f32 v177, v178, v179
	s_waitcnt lgkmcnt(3)
	v_mfma_f32_16x16x32_bf16 v[196:199], v[188:191], v[42:45], v[6:9]
	v_cvt_pk_bf16_f32 v178, v208, v209
	s_nop 1
	v_exp_f32_e32 v192, v192
	v_exp_f32_e32 v193, v193
	v_mfma_f32_16x16x32_bf16 v[184:187], v[184:187], v[46:49], v[14:17]
	s_nop 1
	v_exp_f32_e32 v196, v196
	v_exp_f32_e32 v197, v197
	v_exp_f32_e32 v228, v194
	v_mfma_f32_16x16x32_bf16 v[188:191], v[188:191], v[46:49], v[14:17]
	v_exp_f32_e32 v198, v198
	s_nop 0
	v_exp_f32_e32 v184, v184
	v_exp_f32_e32 v185, v185
	v_mfma_f32_16x16x32_bf16 v[86:89], v[240:243], v[168:171], v[86:89]
	v_exp_f32_e32 v186, v186
	s_nop 1
	v_exp_f32_e32 v188, v188
	v_exp_f32_e32 v189, v189
	v_mfma_f32_16x16x32_bf16 v[78:81], v[172:175], v[168:171], v[78:81]
	v_exp_f32_e32 v190, v190
	v_exp_f32_e32 v187, v187
	v_exp_f32_e32 v191, v191
	s_waitcnt lgkmcnt(1)
	v_mfma_f32_16x16x32_bf16 v[74:77], v[212:215], v[168:171], v[74:77]
	v_cvt_pk_bf16_f32 v179, v210, v211
	v_cvt_pk_bf16_f32 v184, v184, v185
	v_cvt_pk_bf16_f32 v185, v186, v187
	v_mfma_f32_16x16x32_bf16 v[70:73], v[216:219], v[168:171], v[70:73]
	v_cvt_pk_bf16_f32 v186, v188, v189
	v_cvt_pk_bf16_f32 v187, v190, v191
	v_mfma_f32_16x16x32_bf16 v[62:65], v[220:223], v[168:171], v[62:65]
	v_exp_f32_e32 v169, v195
	v_exp_f32_e32 v171, v199
	v_cvt_pk_bf16_f32 v168, v192, v193
	s_waitcnt lgkmcnt(0)
	v_mfma_f32_16x16x32_bf16 v[180:183], v[200:203], v[34:37], v[2:5]
	v_cvt_pk_bf16_f32 v169, v228, v169
	v_cvt_pk_bf16_f32 v170, v196, v197
	v_cvt_pk_bf16_f32 v171, v198, v171
	v_mfma_f32_16x16x32_bf16 v[208:211], v[204:207], v[34:37], v[2:5]
	v_mfma_f32_16x16x32_bf16 v[200:203], v[200:203], v[38:41], v[10:13]
	s_nop 2
	v_exp_f32_e32 v180, v180
	s_nop 2
	v_exp_f32_e32 v188, v208
	v_mfma_f32_16x16x32_bf16 v[204:207], v[204:207], v[38:41], v[10:13]
	v_mfma_f32_16x16x32_bf16 v[122:125], v[172:175], v[176:179], v[122:125]
	v_exp_f32_e32 v190, v202
	s_nop 5
	v_exp_f32_e32 v189, v205
	v_exp_f32_e32 v191, v207
	v_mfma_f32_16x16x32_bf16 v[102:105], v[172:175], v[168:171], v[102:105]
	v_mfma_f32_16x16x32_bf16 v[58:61], v[172:175], v[184:187], v[58:61]
	v_exp_f32_e32 v172, v181
	v_exp_f32_e32 v174, v209
	v_exp_f32_e32 v173, v182
	v_exp_f32_e32 v181, v183
	v_mfma_f32_16x16x32_bf16 v[126:129], v[240:243], v[176:179], v[126:129]
	v_exp_f32_e32 v175, v210
	v_exp_f32_e32 v182, v211
	v_cvt_pk_bf16_f32 v172, v180, v172
	v_mfma_f32_16x16x32_bf16 v[118:121], v[212:215], v[176:179], v[118:121]
	v_cvt_pk_bf16_f32 v173, v173, v181
	v_cvt_pk_bf16_f32 v174, v188, v174
	v_exp_f32_e32 v180, v200
	v_mfma_f32_16x16x32_bf16 v[110:113], v[216:219], v[176:179], v[110:113]
	v_exp_f32_e32 v188, v204
	v_exp_f32_e32 v181, v201
	v_cvt_pk_bf16_f32 v175, v175, v182
	v_mfma_f32_16x16x32_bf16 v[106:109], v[220:223], v[176:179], v[106:109]
	ds_read_b128 v[176:179], v247 offset:14336
	v_mfma_f32_16x16x32_bf16 v[114:117], v[240:243], v[168:171], v[114:117]
	v_mfma_f32_16x16x32_bf16 v[98:101], v[212:215], v[168:171], v[98:101]
	v_mfma_f32_16x16x32_bf16 v[94:97], v[216:219], v[168:171], v[94:97]
	v_mfma_f32_16x16x32_bf16 v[90:93], v[220:223], v[168:171], v[90:93]
	v_exp_f32_e32 v171, v206
	v_exp_f32_e32 v169, v203
	v_mfma_f32_16x16x32_bf16 v[82:85], v[240:243], v[184:187], v[82:85]
	v_cvt_pk_bf16_f32 v168, v180, v181
	ds_read_b64 v[180:181], v248 offset:9280
	ds_read_b64 v[182:183], v248 offset:9312
	v_cvt_pk_bf16_f32 v170, v188, v189
	v_mfma_f32_16x16x32_bf16 v[54:57], v[212:215], v[184:187], v[54:57]
	v_cvt_pk_bf16_f32 v169, v190, v169
	v_cvt_pk_bf16_f32 v171, v171, v191
	v_mfma_f32_16x16x32_bf16 v[50:53], v[216:219], v[184:187], v[50:53]
	ds_read_b64 v[188:189], v248 offset:13888
	ds_read_b64 v[190:191], v248 offset:13920
	ds_read_b64 v[200:201], v248 offset:16192
	ds_read_b64 v[202:203], v248 offset:16224
	v_mfma_f32_16x16x32_bf16 v[66:69], v[220:223], v[184:187], v[66:69]
	ds_read_b64 v[184:185], v248 offset:11584
	ds_read_b64 v[186:187], v248 offset:11616
	v_mfma_f32_16x16x32_bf16 v[192:195], v[224:227], v[42:45], v[6:9]
	s_waitcnt lgkmcnt(8)
	v_mfma_f32_16x16x32_bf16 v[196:199], v[176:179], v[42:45], v[6:9]
	v_mfma_f32_16x16x32_bf16 v[224:227], v[224:227], v[46:49], v[14:17]
	s_nop 4
	v_exp_f32_e32 v192, v192
	s_nop 0
	v_exp_f32_e32 v196, v196
	v_exp_f32_e32 v193, v193
	v_mfma_f32_16x16x32_bf16 v[176:179], v[176:179], v[46:49], v[14:17]
	v_exp_f32_e32 v197, v197
	v_exp_f32_e32 v194, v194
	v_exp_f32_e32 v195, v195
	v_mfma_f32_16x16x32_bf16 v[126:129], v[240:243], v[172:175], v[126:129]
	v_exp_f32_e32 v198, v198
	v_exp_f32_e32 v199, v199
	v_cvt_pk_bf16_f32 v192, v192, v193
	v_mfma_f32_16x16x32_bf16 v[86:89], v[240:243], v[168:171], v[86:89]
	v_cvt_pk_bf16_f32 v193, v194, v195
	v_cvt_pk_bf16_f32 v194, v196, v197
	v_exp_f32_e32 v196, v224
	s_waitcnt lgkmcnt(6)
	v_mfma_f32_16x16x32_bf16 v[122:125], v[180:183], v[172:175], v[122:125]
	v_exp_f32_e32 v176, v176
	v_exp_f32_e32 v197, v225
	v_cvt_pk_bf16_f32 v195, v198, v199
	v_mfma_f32_16x16x32_bf16 v[78:81], v[180:183], v[168:171], v[78:81]
	s_waitcnt lgkmcnt(0)
	v_mfma_f32_16x16x32_bf16 v[118:121], v[184:187], v[172:175], v[118:121]
	v_mfma_f32_16x16x32_bf16 v[74:77], v[184:187], v[168:171], v[74:77]
	v_mfma_f32_16x16x32_bf16 v[110:113], v[188:191], v[172:175], v[110:113]
	v_mfma_f32_16x16x32_bf16 v[70:73], v[188:191], v[168:171], v[70:73]
	v_mfma_f32_16x16x32_bf16 v[106:109], v[200:203], v[172:175], v[106:109]
	v_exp_f32_e32 v172, v177
	v_exp_f32_e32 v173, v226
	v_exp_f32_e32 v174, v178
	v_mfma_f32_16x16x32_bf16 v[62:65], v[200:203], v[168:171], v[62:65]
	v_exp_f32_e32 v169, v227
	v_exp_f32_e32 v171, v179
	v_cvt_pk_bf16_f32 v168, v196, v197
	v_cvt_pk_bf16_f32 v170, v176, v172
	v_cvt_pk_bf16_f32 v169, v173, v169
	v_cvt_pk_bf16_f32 v171, v174, v171
	v_mfma_f32_16x16x32_bf16 v[114:117], v[240:243], v[192:195], v[114:117]
	s_nop 0
	v_mfma_f32_16x16x32_bf16 v[82:85], v[240:243], v[168:171], v[82:85]
	v_mfma_f32_16x16x32_bf16 v[102:105], v[180:183], v[192:195], v[102:105]
	v_mfma_f32_16x16x32_bf16 v[58:61], v[180:183], v[168:171], v[58:61]
	v_mfma_f32_16x16x32_bf16 v[98:101], v[184:187], v[192:195], v[98:101]
	v_mfma_f32_16x16x32_bf16 v[54:57], v[184:187], v[168:171], v[54:57]
	v_mfma_f32_16x16x32_bf16 v[94:97], v[188:191], v[192:195], v[94:97]
	v_mfma_f32_16x16x32_bf16 v[50:53], v[188:191], v[168:171], v[50:53]
	v_mfma_f32_16x16x32_bf16 v[90:93], v[200:203], v[192:195], v[90:93]
	v_mfma_f32_16x16x32_bf16 v[66:69], v[200:203], v[168:171], v[66:69]
	s_cbranch_vccnz .LBB0_928
.Ldiff_hB_925:
	s_and_b32 s0, s12, 0x80
	s_lshl_b32 s1, s0, 7
	s_add_i32 s39, s1, 0
	s_lshl_b32 s0, s0, 4
	s_add_i32 s2, s39, s0
	s_cmpk_gt_u32 s38, 0x101
	s_cselect_b64 s[0:1], -1, 0
	s_and_b64 vcc, exec, s[0:1]
	s_waitcnt vmcnt(3)
	ds_write_b128 v244, v[18:21] offset:16384
	s_waitcnt vmcnt(1)
	ds_write_b128 v245, v[22:25] offset:18432
	s_waitcnt vmcnt(1)
	ds_write_b128 v244, v[26:29] offset:24576
	s_waitcnt vmcnt(0)
	ds_write_b128 v245, v[30:33] offset:27648
	s_waitcnt lgkmcnt(0)
	s_barrier
	ds_read_b128 v[130:133], v246 offset:16384
	ds_read_b128 v[168:171], v246 offset:18432
	s_cbranch_vccnz .Ldiff_bB_925
	s_cmp_eq_u32 s12, 0
	s_cbranch_scc0 .Lpf_nextB_925
	v_add_u32_e32 v250, s36, v161
	v_mad_i64_i32 v[250:251], s[40:41], v250, s21, v[146:147]
	v_add_u32_e32 v252, s37, v161
	v_mad_i64_i32 v[252:253], s[40:41], v252, s21, v[146:147]
	s_sub_i32 s100, s35, s36
	s_mul_hi_i32 s101, s100, 0x1640
	s_mul_i32 s100, s100, 0x1640
	s_branch .Lpf_loadB_925

.Ldiff_bB_925:
	s_waitcnt lgkmcnt(1)
	v_mfma_f32_16x16x32_bf16 v[172:175], v[130:133], v[34:37], v[2:5]
	ds_read_b128 v[184:187], v247 offset:18432
	v_mfma_f32_16x16x32_bf16 v[180:183], v[130:133], v[38:41], v[10:13]
	ds_read_b128 v[130:133], v247 offset:16384
	s_nop 2
	s_nop 1
	v_exp_f32_e32 v200, v172
	v_exp_f32_e32 v201, v175
	s_waitcnt lgkmcnt(2)
	v_mfma_f32_16x16x32_bf16 v[176:179], v[168:171], v[34:37], v[2:5]
	v_exp_f32_e32 v180, v180
	ds_read_b64 v[216:217], v248 offset:23040
	ds_read_b64 v[218:219], v248 offset:23072
	v_mfma_f32_16x16x32_bf16 v[168:171], v[168:171], v[38:41], v[10:13]
	ds_read_b64 v[220:221], v248 offset:25344
	ds_read_b64 v[222:223], v248 offset:25376
	s_nop 2
	v_exp_f32_e32 v204, v176
	v_exp_f32_e32 v176, v173
	s_waitcnt lgkmcnt(4)
	v_mfma_f32_16x16x32_bf16 v[188:191], v[130:133], v[42:45], v[6:9]
	v_exp_f32_e32 v205, v177
	v_exp_f32_e32 v213, v168
	v_exp_f32_e32 v168, v181
	v_mfma_f32_16x16x32_bf16 v[196:199], v[130:133], v[46:49], v[14:17]
	ds_read_b128 v[130:133], v246 offset:20480
	v_exp_f32_e32 v181, v169
	v_exp_f32_e32 v169, v182
	v_exp_f32_e32 v182, v170
	v_exp_f32_e32 v170, v183
	v_exp_f32_e32 v171, v171
	v_exp_f32_e32 v177, v174
	v_cvt_pk_bf16_f32 v168, v180, v168
	v_cvt_pk_bf16_f32 v169, v169, v170
	v_cvt_pk_bf16_f32 v170, v213, v181
	v_cvt_pk_bf16_f32 v171, v182, v171
	ds_read_b64 v[180:181], v248 offset:18432
	ds_read_b64 v[182:183], v248 offset:18464
	ds_read_b64 v[212:213], v248 offset:20736
	ds_read_b64 v[214:215], v248 offset:20768
	ds_read_b128 v[172:175], v246 offset:22528
	v_cvt_pk_bf16_f32 v176, v200, v176
	v_cvt_pk_bf16_f32 v177, v177, v201
	s_waitcnt lgkmcnt(5)
	v_mfma_f32_16x16x32_bf16 v[200:203], v[130:133], v[34:37], v[2:5]
	v_exp_f32_e32 v231, v190
	v_exp_f32_e32 v206, v178
	v_exp_f32_e32 v179, v179
	v_mfma_f32_16x16x32_bf16 v[208:211], v[130:133], v[38:41], v[10:13]
	v_exp_f32_e32 v188, v188
	v_mfma_f32_16x16x32_bf16 v[192:195], v[184:187], v[42:45], v[6:9]
	v_exp_f32_e32 v189, v189
	v_exp_f32_e32 v196, v196
	v_cvt_pk_bf16_f32 v178, v204, v205
	v_mfma_f32_16x16x32_bf16 v[184:187], v[184:187], v[46:49], v[14:17]
	v_cvt_pk_bf16_f32 v179, v206, v179
	s_nop 2
	v_exp_f32_e32 v192, v192
	v_exp_f32_e32 v193, v193
	v_mfma_f32_16x16x32_bf16 v[86:89], v[240:243], v[168:171], v[86:89]
	v_exp_f32_e32 v194, v194
	v_exp_f32_e32 v187, v187
	ds_read_b128 v[224:227], v247 offset:20480
	s_waitcnt lgkmcnt(4)
	v_mfma_f32_16x16x32_bf16 v[78:81], v[180:183], v[168:171], v[78:81]
	s_add_i32 s38, s38, 2
	s_addk_i32 s12, 0x80
	v_lshl_add_u64 v[148:149], v[148:149], 0, s[16:17]
	s_waitcnt lgkmcnt(2)
	v_mfma_f32_16x16x32_bf16 v[74:77], v[212:215], v[168:171], v[74:77]
	s_and_b64 vcc, exec, s[0:1]
	v_mfma_f32_16x16x32_bf16 v[70:73], v[216:219], v[168:171], v[70:73]
	v_mfma_f32_16x16x32_bf16 v[62:65], v[220:223], v[168:171], v[62:65]
	v_exp_f32_e32 v169, v191
	v_exp_f32_e32 v171, v195
	v_cvt_pk_bf16_f32 v168, v188, v189
	s_waitcnt lgkmcnt(1)
	v_mfma_f32_16x16x32_bf16 v[204:207], v[172:175], v[34:37], v[2:5]
	v_cvt_pk_bf16_f32 v169, v231, v169
	v_exp_f32_e32 v231, v184
	v_exp_f32_e32 v184, v197
	v_exp_f32_e32 v197, v185
	v_exp_f32_e32 v185, v198
	v_exp_f32_e32 v198, v186
	v_exp_f32_e32 v186, v199
	v_cvt_pk_bf16_f32 v170, v192, v193
	v_cvt_pk_bf16_f32 v171, v194, v171
	v_cvt_pk_bf16_f32 v184, v196, v184
	v_cvt_pk_bf16_f32 v185, v185, v186
	v_cvt_pk_bf16_f32 v186, v231, v197
	v_cvt_pk_bf16_f32 v187, v198, v187
	v_mfma_f32_16x16x32_bf16 v[172:175], v[172:175], v[38:41], v[10:13]
	v_exp_f32_e32 v196, v200
	v_exp_f32_e32 v197, v204
	v_exp_f32_e32 v198, v201
	v_mfma_f32_16x16x32_bf16 v[122:125], v[180:183], v[176:179], v[122:125]
	v_exp_f32_e32 v200, v207
	v_exp_f32_e32 v199, v203
	v_mfma_f32_16x16x32_bf16 v[102:105], v[180:183], v[168:171], v[102:105]
	v_mfma_f32_16x16x32_bf16 v[58:61], v[180:183], v[184:187], v[58:61]
	v_exp_f32_e32 v182, v205
	v_exp_f32_e32 v183, v206
	v_exp_f32_e32 v181, v202
	v_mfma_f32_16x16x32_bf16 v[126:129], v[240:243], v[176:179], v[126:129]
	v_cvt_pk_bf16_f32 v180, v196, v198
	v_cvt_pk_bf16_f32 v182, v197, v182
	v_cvt_pk_bf16_f32 v183, v183, v200
	v_mfma_f32_16x16x32_bf16 v[118:121], v[212:215], v[176:179], v[118:121]
	v_exp_f32_e32 v196, v208
	v_exp_f32_e32 v197, v172
	v_exp_f32_e32 v172, v209
	v_mfma_f32_16x16x32_bf16 v[110:113], v[216:219], v[176:179], v[110:113]
	v_exp_f32_e32 v200, v174
	v_cvt_pk_bf16_f32 v181, v181, v199
	v_exp_f32_e32 v198, v173
	v_mfma_f32_16x16x32_bf16 v[106:109], v[220:223], v[176:179], v[106:109]
	ds_read_b128 v[176:179], v247 offset:22528
	v_exp_f32_e32 v199, v210
	ds_read_b128 v[204:207], v246 offset:30720
	v_mfma_f32_16x16x32_bf16 v[114:117], v[240:243], v[168:171], v[114:117]
	v_mfma_f32_16x16x32_bf16 v[98:101], v[212:215], v[168:171], v[98:101]
	v_mfma_f32_16x16x32_bf16 v[94:97], v[216:219], v[168:171], v[94:97]
	v_mfma_f32_16x16x32_bf16 v[90:93], v[220:223], v[168:171], v[90:93]
	v_exp_f32_e32 v171, v175
	v_exp_f32_e32 v169, v211
	v_cvt_pk_bf16_f32 v168, v196, v172
	v_mfma_f32_16x16x32_bf16 v[82:85], v[240:243], v[184:187], v[82:85]
	v_cvt_pk_bf16_f32 v171, v200, v171
	v_mfma_f32_16x16x32_bf16 v[54:57], v[212:215], v[184:187], v[54:57]
	ds_read_b64 v[172:173], v248 offset:18496
	ds_read_b64 v[174:175], v248 offset:18528
	v_cvt_pk_bf16_f32 v169, v199, v169
	v_mfma_f32_16x16x32_bf16 v[50:53], v[216:219], v[184:187], v[50:53]
	v_cvt_pk_bf16_f32 v170, v197, v198
	ds_read_b64 v[196:197], v248 offset:23104
	ds_read_b64 v[198:199], v248 offset:23136
	ds_read_b64 v[200:201], v248 offset:25408
	ds_read_b64 v[202:203], v248 offset:25440
	v_mfma_f32_16x16x32_bf16 v[66:69], v[220:223], v[184:187], v[66:69]
	ds_read_b64 v[184:185], v248 offset:20800
	ds_read_b64 v[186:187], v248 offset:20832
	s_waitcnt lgkmcnt(10)
	v_mfma_f32_16x16x32_bf16 v[188:191], v[224:227], v[42:45], v[6:9]
	ds_read_b64 v[216:217], v248 offset:32256
	ds_read_b64 v[218:219], v248 offset:32288
	s_waitcnt lgkmcnt(11)
	v_mfma_f32_16x16x32_bf16 v[192:195], v[176:179], v[42:45], v[6:9]
	ds_read_b64 v[220:221], v248 offset:34560
	ds_read_b64 v[222:223], v248 offset:34592
	s_nop 1
	v_exp_f32_e32 v188, v188
	v_exp_f32_e32 v189, v189
	v_mfma_f32_16x16x32_bf16 v[224:227], v[224:227], v[46:49], v[14:17]
	v_exp_f32_e32 v190, v190
	s_nop 0
	v_exp_f32_e32 v192, v192
	v_exp_f32_e32 v193, v193
	v_mfma_f32_16x16x32_bf16 v[176:179], v[176:179], v[46:49], v[14:17]
	v_exp_f32_e32 v191, v191
	v_exp_f32_e32 v194, v194
	v_exp_f32_e32 v195, v195
	v_mfma_f32_16x16x32_bf16 v[126:129], v[240:243], v[180:183], v[126:129]
	v_cvt_pk_bf16_f32 v188, v188, v189
	v_cvt_pk_bf16_f32 v189, v190, v191
	v_cvt_pk_bf16_f32 v190, v192, v193
	v_mfma_f32_16x16x32_bf16 v[86:89], v[240:243], v[168:171], v[86:89]
	v_exp_f32_e32 v192, v224
	v_exp_f32_e32 v176, v176
	v_exp_f32_e32 v193, v225
	s_waitcnt lgkmcnt(10)
	v_mfma_f32_16x16x32_bf16 v[122:125], v[172:175], v[180:183], v[122:125]
	v_exp_f32_e32 v177, v177
	v_exp_f32_e32 v178, v178
	v_cvt_pk_bf16_f32 v191, v194, v195
	v_mfma_f32_16x16x32_bf16 v[78:81], v[172:175], v[168:171], v[78:81]
	s_waitcnt lgkmcnt(4)
	v_mfma_f32_16x16x32_bf16 v[118:121], v[184:187], v[180:183], v[118:121]
	v_mfma_f32_16x16x32_bf16 v[74:77], v[184:187], v[168:171], v[74:77]
	v_mfma_f32_16x16x32_bf16 v[110:113], v[196:199], v[180:183], v[110:113]
	v_mfma_f32_16x16x32_bf16 v[70:73], v[196:199], v[168:171], v[70:73]
	v_mfma_f32_16x16x32_bf16 v[106:109], v[200:203], v[180:183], v[106:109]
	v_exp_f32_e32 v180, v226
	v_mfma_f32_16x16x32_bf16 v[62:65], v[200:203], v[168:171], v[62:65]
	v_exp_f32_e32 v169, v227
	v_exp_f32_e32 v171, v179
	v_cvt_pk_bf16_f32 v168, v192, v193
	v_cvt_pk_bf16_f32 v170, v176, v177
	v_cvt_pk_bf16_f32 v169, v180, v169
	v_cvt_pk_bf16_f32 v171, v178, v171
	v_mfma_f32_16x16x32_bf16 v[102:105], v[172:175], v[188:191], v[102:105]
	ds_read_b128 v[224:227], v247 offset:28672
	v_mfma_f32_16x16x32_bf16 v[82:85], v[240:243], v[168:171], v[82:85]
	v_mfma_f32_16x16x32_bf16 v[58:61], v[172:175], v[168:171], v[58:61]
	ds_read_b128 v[172:175], v246 offset:24576
	v_mfma_f32_16x16x32_bf16 v[54:57], v[184:187], v[168:171], v[54:57]
	v_mfma_f32_16x16x32_bf16 v[50:53], v[196:199], v[168:171], v[50:53]
	v_mfma_f32_16x16x32_bf16 v[66:69], v[200:203], v[168:171], v[66:69]
	ds_read_b128 v[168:171], v246 offset:26624
	s_waitcnt lgkmcnt(1)
	v_mfma_f32_16x16x32_bf16 v[176:179], v[172:175], v[34:37], v[2:5]
	s_waitcnt lgkmcnt(0)
	v_mfma_f32_16x16x32_bf16 v[180:183], v[168:171], v[34:37], v[2:5]
	s_nop 5
	v_exp_f32_e32 v176, v176
	v_mfma_f32_16x16x32_bf16 v[172:175], v[172:175], v[38:41], v[10:13]
	v_exp_f32_e32 v208, v180
	v_exp_f32_e32 v177, v177
	v_exp_f32_e32 v209, v181
	v_mfma_f32_16x16x32_bf16 v[168:171], v[168:171], v[38:41], v[10:13]
	v_exp_f32_e32 v178, v178
	s_nop 2
	v_exp_f32_e32 v172, v172
	v_exp_f32_e32 v210, v182
	v_mfma_f32_16x16x32_bf16 v[114:117], v[240:243], v[188:191], v[114:117]
	v_exp_f32_e32 v179, v179
	v_exp_f32_e32 v213, v168
	v_exp_f32_e32 v168, v173
	v_exp_f32_e32 v173, v169
	v_exp_f32_e32 v169, v174
	v_exp_f32_e32 v174, v170
	v_exp_f32_e32 v170, v175
	v_exp_f32_e32 v171, v171
	v_mfma_f32_16x16x32_bf16 v[98:101], v[184:187], v[188:191], v[98:101]
	ds_read_b128 v[184:187], v247 offset:24576
	v_cvt_pk_bf16_f32 v168, v172, v168
	v_cvt_pk_bf16_f32 v169, v169, v170
	v_mfma_f32_16x16x32_bf16 v[94:97], v[196:199], v[188:191], v[94:97]
	v_cvt_pk_bf16_f32 v170, v213, v173
	v_cvt_pk_bf16_f32 v171, v174, v171
	ds_read_b64 v[172:173], v248 offset:27648
	ds_read_b64 v[174:175], v248 offset:27680
	v_mfma_f32_16x16x32_bf16 v[90:93], v[200:203], v[188:191], v[90:93]
	ds_read_b128 v[188:191], v247 offset:26624
	ds_read_b64 v[212:213], v248 offset:29952
	ds_read_b64 v[214:215], v248 offset:29984
	ds_read_b128 v[200:203], v246 offset:28672
	s_waitcnt lgkmcnt(6)
	v_mfma_f32_16x16x32_bf16 v[192:195], v[184:187], v[42:45], v[6:9]
	v_exp_f32_e32 v211, v183
	v_cvt_pk_bf16_f32 v176, v176, v177
	v_cvt_pk_bf16_f32 v177, v178, v179
	s_waitcnt lgkmcnt(3)
	v_mfma_f32_16x16x32_bf16 v[196:199], v[188:191], v[42:45], v[6:9]
	v_cvt_pk_bf16_f32 v178, v208, v209
	s_nop 1
	v_exp_f32_e32 v192, v192
	v_exp_f32_e32 v193, v193
	v_mfma_f32_16x16x32_bf16 v[184:187], v[184:187], v[46:49], v[14:17]
	s_nop 1
	v_exp_f32_e32 v196, v196
	v_exp_f32_e32 v197, v197
	v_exp_f32_e32 v228, v194
	v_mfma_f32_16x16x32_bf16 v[188:191], v[188:191], v[46:49], v[14:17]
	v_exp_f32_e32 v198, v198
	s_nop 0
	v_exp_f32_e32 v184, v184
	v_exp_f32_e32 v185, v185
	v_mfma_f32_16x16x32_bf16 v[86:89], v[240:243], v[168:171], v[86:89]
	v_exp_f32_e32 v186, v186
	s_nop 1
	v_exp_f32_e32 v188, v188
	v_exp_f32_e32 v189, v189
	v_mfma_f32_16x16x32_bf16 v[78:81], v[172:175], v[168:171], v[78:81]
	v_exp_f32_e32 v190, v190
	v_exp_f32_e32 v187, v187
	v_exp_f32_e32 v191, v191
	s_waitcnt lgkmcnt(1)
	v_mfma_f32_16x16x32_bf16 v[74:77], v[212:215], v[168:171], v[74:77]
	v_cvt_pk_bf16_f32 v179, v210, v211
	v_cvt_pk_bf16_f32 v184, v184, v185
	v_cvt_pk_bf16_f32 v185, v186, v187
	v_mfma_f32_16x16x32_bf16 v[70:73], v[216:219], v[168:171], v[70:73]
	v_cvt_pk_bf16_f32 v186, v188, v189
	v_cvt_pk_bf16_f32 v187, v190, v191
	v_mfma_f32_16x16x32_bf16 v[62:65], v[220:223], v[168:171], v[62:65]
	v_exp_f32_e32 v169, v195
	v_exp_f32_e32 v171, v199
	v_cvt_pk_bf16_f32 v168, v192, v193
	s_waitcnt lgkmcnt(0)
	v_mfma_f32_16x16x32_bf16 v[180:183], v[200:203], v[34:37], v[2:5]
	v_cvt_pk_bf16_f32 v169, v228, v169
	v_cvt_pk_bf16_f32 v170, v196, v197
	v_cvt_pk_bf16_f32 v171, v198, v171
	v_mfma_f32_16x16x32_bf16 v[208:211], v[204:207], v[34:37], v[2:5]
	v_mfma_f32_16x16x32_bf16 v[200:203], v[200:203], v[38:41], v[10:13]
	s_nop 2
	v_exp_f32_e32 v180, v180
	s_nop 2
	v_exp_f32_e32 v188, v208
	v_mfma_f32_16x16x32_bf16 v[204:207], v[204:207], v[38:41], v[10:13]
	v_mfma_f32_16x16x32_bf16 v[122:125], v[172:175], v[176:179], v[122:125]
	v_exp_f32_e32 v190, v202
	s_nop 5
	v_exp_f32_e32 v189, v205
	v_exp_f32_e32 v191, v207
	v_mfma_f32_16x16x32_bf16 v[102:105], v[172:175], v[168:171], v[102:105]
	v_mfma_f32_16x16x32_bf16 v[58:61], v[172:175], v[184:187], v[58:61]
	v_exp_f32_e32 v172, v181
	v_exp_f32_e32 v174, v209
	v_exp_f32_e32 v173, v182
	v_exp_f32_e32 v181, v183
	v_mfma_f32_16x16x32_bf16 v[126:129], v[240:243], v[176:179], v[126:129]
	v_exp_f32_e32 v175, v210
	v_exp_f32_e32 v182, v211
	v_cvt_pk_bf16_f32 v172, v180, v172
	v_mfma_f32_16x16x32_bf16 v[118:121], v[212:215], v[176:179], v[118:121]
	v_cvt_pk_bf16_f32 v173, v173, v181
	v_cvt_pk_bf16_f32 v174, v188, v174
	v_exp_f32_e32 v180, v200
	v_mfma_f32_16x16x32_bf16 v[110:113], v[216:219], v[176:179], v[110:113]
	v_exp_f32_e32 v188, v204
	v_exp_f32_e32 v181, v201
	v_cvt_pk_bf16_f32 v175, v175, v182
	v_mfma_f32_16x16x32_bf16 v[106:109], v[220:223], v[176:179], v[106:109]
	ds_read_b128 v[176:179], v247 offset:30720
	v_mfma_f32_16x16x32_bf16 v[114:117], v[240:243], v[168:171], v[114:117]
	v_mfma_f32_16x16x32_bf16 v[98:101], v[212:215], v[168:171], v[98:101]
	v_mfma_f32_16x16x32_bf16 v[94:97], v[216:219], v[168:171], v[94:97]
	v_mfma_f32_16x16x32_bf16 v[90:93], v[220:223], v[168:171], v[90:93]
	v_exp_f32_e32 v171, v206
	v_exp_f32_e32 v169, v203
	v_mfma_f32_16x16x32_bf16 v[82:85], v[240:243], v[184:187], v[82:85]
	v_cvt_pk_bf16_f32 v168, v180, v181
	ds_read_b64 v[180:181], v248 offset:27712
	ds_read_b64 v[182:183], v248 offset:27744
	v_cvt_pk_bf16_f32 v170, v188, v189
	v_mfma_f32_16x16x32_bf16 v[54:57], v[212:215], v[184:187], v[54:57]
	v_cvt_pk_bf16_f32 v169, v190, v169
	v_cvt_pk_bf16_f32 v171, v171, v191
	v_mfma_f32_16x16x32_bf16 v[50:53], v[216:219], v[184:187], v[50:53]
	ds_read_b64 v[188:189], v248 offset:32320
	ds_read_b64 v[190:191], v248 offset:32352
	ds_read_b64 v[200:201], v248 offset:34624
	ds_read_b64 v[202:203], v248 offset:34656
	v_mfma_f32_16x16x32_bf16 v[66:69], v[220:223], v[184:187], v[66:69]
	ds_read_b64 v[184:185], v248 offset:30016
	ds_read_b64 v[186:187], v248 offset:30048
	v_mfma_f32_16x16x32_bf16 v[192:195], v[224:227], v[42:45], v[6:9]
	s_waitcnt lgkmcnt(8)
	v_mfma_f32_16x16x32_bf16 v[196:199], v[176:179], v[42:45], v[6:9]
	v_mfma_f32_16x16x32_bf16 v[224:227], v[224:227], v[46:49], v[14:17]
	s_nop 4
	v_exp_f32_e32 v192, v192
	s_nop 0
	v_exp_f32_e32 v196, v196
	v_exp_f32_e32 v193, v193
	v_mfma_f32_16x16x32_bf16 v[176:179], v[176:179], v[46:49], v[14:17]
	v_exp_f32_e32 v197, v197
	v_exp_f32_e32 v194, v194
	v_exp_f32_e32 v195, v195
	v_mfma_f32_16x16x32_bf16 v[126:129], v[240:243], v[172:175], v[126:129]
	v_exp_f32_e32 v198, v198
	v_exp_f32_e32 v199, v199
	v_cvt_pk_bf16_f32 v192, v192, v193
	v_mfma_f32_16x16x32_bf16 v[86:89], v[240:243], v[168:171], v[86:89]
	v_cvt_pk_bf16_f32 v193, v194, v195
	v_cvt_pk_bf16_f32 v194, v196, v197
	v_exp_f32_e32 v196, v224
	s_waitcnt lgkmcnt(6)
	v_mfma_f32_16x16x32_bf16 v[122:125], v[180:183], v[172:175], v[122:125]
	v_exp_f32_e32 v176, v176
	v_exp_f32_e32 v197, v225
	v_cvt_pk_bf16_f32 v195, v198, v199
	v_mfma_f32_16x16x32_bf16 v[78:81], v[180:183], v[168:171], v[78:81]
	s_waitcnt lgkmcnt(0)
	v_mfma_f32_16x16x32_bf16 v[118:121], v[184:187], v[172:175], v[118:121]
	v_mfma_f32_16x16x32_bf16 v[74:77], v[184:187], v[168:171], v[74:77]
	v_mfma_f32_16x16x32_bf16 v[110:113], v[188:191], v[172:175], v[110:113]
	v_mfma_f32_16x16x32_bf16 v[70:73], v[188:191], v[168:171], v[70:73]
	v_mfma_f32_16x16x32_bf16 v[106:109], v[200:203], v[172:175], v[106:109]
	v_exp_f32_e32 v172, v177
	v_exp_f32_e32 v173, v226
	v_exp_f32_e32 v174, v178
	v_mfma_f32_16x16x32_bf16 v[62:65], v[200:203], v[168:171], v[62:65]
	v_exp_f32_e32 v169, v227
	v_exp_f32_e32 v171, v179
	v_cvt_pk_bf16_f32 v168, v196, v197
	v_cvt_pk_bf16_f32 v170, v176, v172
	v_cvt_pk_bf16_f32 v169, v173, v169
	v_cvt_pk_bf16_f32 v171, v174, v171
	v_mfma_f32_16x16x32_bf16 v[114:117], v[240:243], v[192:195], v[114:117]
	s_nop 0
	v_mfma_f32_16x16x32_bf16 v[82:85], v[240:243], v[168:171], v[82:85]
	v_mfma_f32_16x16x32_bf16 v[102:105], v[180:183], v[192:195], v[102:105]
	v_mfma_f32_16x16x32_bf16 v[58:61], v[180:183], v[168:171], v[58:61]
	v_mfma_f32_16x16x32_bf16 v[98:101], v[184:187], v[192:195], v[98:101]
	v_mfma_f32_16x16x32_bf16 v[54:57], v[184:187], v[168:171], v[54:57]
	v_mfma_f32_16x16x32_bf16 v[94:97], v[188:191], v[192:195], v[94:97]
	v_mfma_f32_16x16x32_bf16 v[50:53], v[188:191], v[168:171], v[50:53]
	v_mfma_f32_16x16x32_bf16 v[90:93], v[200:203], v[192:195], v[90:93]
	v_mfma_f32_16x16x32_bf16 v[66:69], v[200:203], v[168:171], v[66:69]
	s_cbranch_vccnz .LBB0_928
.LBB0_926:
	s_and_b32 s0, s12, 0x80
	s_lshl_b32 s1, s0, 7
	s_add_i32 s39, s1, 0
	s_lshl_b32 s0, s0, 4
	s_add_i32 s2, s39, s0
	s_cmpk_gt_u32 s38, 0x101
	s_cselect_b64 s[0:1], -1, 0
	s_and_b64 vcc, exec, s[0:1]
	s_waitcnt vmcnt(3)
	ds_write_b128 v244, v[18:21]
	s_waitcnt vmcnt(1)
	ds_write_b128 v245, v[22:25] offset:0
	s_waitcnt vmcnt(1)
	ds_write_b128 v244, v[26:29] offset:8192
	s_waitcnt vmcnt(0)
	ds_write_b128 v245, v[30:33] offset:9216
	s_waitcnt lgkmcnt(0)
	s_barrier
	ds_read_b128 v[130:133], v246
	ds_read_b128 v[168:171], v246 offset:2048
	s_cbranch_vccnz .LBB0_925
	s_cmp_eq_u32 s12, 0
	s_cbranch_scc0 .Lpf_next_925
	v_add_u32_e32 v250, s36, v161
	v_mad_i64_i32 v[250:251], s[40:41], v250, s21, v[146:147]
	v_add_u32_e32 v252, s37, v161
	v_mad_i64_i32 v[252:253], s[40:41], v252, s21, v[146:147]
	s_sub_i32 s100, s35, s36
	s_mul_hi_i32 s101, s100, 0x1640
	s_mul_i32 s100, s100, 0x1640
	s_branch .Lpf_load_925

.Lnoprio_2159:
	v_add_u32_e32 v248, 0x8000, v248
	v_add_u32_e32 v245, 0x8000, v245
	v_lshlrev_b32_e32 v134, 1, v158
	s_barrier
	s_branch .LBB0_2160
.LBB0_2159:
	s_waitcnt lgkmcnt(1)
	v_mfma_f32_16x16x32_bf16 v[170:173], v[130:133], v[34:37], v[2:5]
	ds_read_b128 v[182:185], v247 offset:2048
	v_mfma_f32_16x16x32_bf16 v[178:181], v[130:133], v[38:41], v[10:13]
	ds_read_b128 v[130:133], v247
	s_nop 2
	s_nop 1
	v_exp_f32_e32 v198, v170
	v_exp_f32_e32 v199, v173
	s_waitcnt lgkmcnt(2)
	v_mfma_f32_16x16x32_bf16 v[174:177], v[166:169], v[34:37], v[2:5]
	v_exp_f32_e32 v178, v178
	ds_read_b64 v[214:215], v248 offset:4608
	ds_read_b64 v[216:217], v248 offset:4640
	v_mfma_f32_16x16x32_bf16 v[166:169], v[166:169], v[38:41], v[10:13]
	ds_read_b64 v[218:219], v248 offset:6912
	ds_read_b64 v[220:221], v248 offset:6944
	s_nop 2
	v_exp_f32_e32 v202, v174
	v_exp_f32_e32 v174, v171
	s_waitcnt lgkmcnt(4)
	v_mfma_f32_16x16x32_bf16 v[186:189], v[130:133], v[42:45], v[6:9]
	v_exp_f32_e32 v203, v175
	v_exp_f32_e32 v211, v166
	v_exp_f32_e32 v166, v179
	v_mfma_f32_16x16x32_bf16 v[194:197], v[130:133], v[46:49], v[14:17]
	ds_read_b128 v[130:133], v246 offset:4096
	v_exp_f32_e32 v179, v167
	v_exp_f32_e32 v167, v180
	v_exp_f32_e32 v180, v168
	v_exp_f32_e32 v168, v181
	v_exp_f32_e32 v169, v169
	v_exp_f32_e32 v175, v172
	v_cvt_pk_bf16_f32 v166, v178, v166
	v_cvt_pk_bf16_f32 v167, v167, v168
	v_cvt_pk_bf16_f32 v168, v211, v179
	v_cvt_pk_bf16_f32 v169, v180, v169
	ds_read_b64 v[178:179], v248 offset:0
	ds_read_b64 v[180:181], v248 offset:32
	ds_read_b64 v[210:211], v248 offset:2304
	ds_read_b64 v[212:213], v248 offset:2336
	ds_read_b128 v[170:173], v246 offset:6144
	v_cvt_pk_bf16_f32 v174, v198, v174
	v_cvt_pk_bf16_f32 v175, v175, v199
	s_waitcnt lgkmcnt(5)
	v_mfma_f32_16x16x32_bf16 v[198:201], v[130:133], v[34:37], v[2:5]
	v_exp_f32_e32 v229, v188
	v_exp_f32_e32 v204, v176
	v_exp_f32_e32 v177, v177
	v_mfma_f32_16x16x32_bf16 v[206:209], v[130:133], v[38:41], v[10:13]
	v_exp_f32_e32 v186, v186
	v_mfma_f32_16x16x32_bf16 v[190:193], v[182:185], v[42:45], v[6:9]
	v_exp_f32_e32 v187, v187
	v_exp_f32_e32 v194, v194
	v_cvt_pk_bf16_f32 v176, v202, v203
	v_mfma_f32_16x16x32_bf16 v[182:185], v[182:185], v[46:49], v[14:17]
	v_cvt_pk_bf16_f32 v177, v204, v177
	s_nop 2
	v_exp_f32_e32 v190, v190
	v_exp_f32_e32 v191, v191
	v_mfma_f32_16x16x32_bf16 v[86:89], v[240:243], v[166:169], v[86:89]
	v_exp_f32_e32 v192, v192
	v_exp_f32_e32 v185, v185
	ds_read_b128 v[222:225], v247 offset:4096
	s_waitcnt lgkmcnt(4)
	v_mfma_f32_16x16x32_bf16 v[78:81], v[178:181], v[166:169], v[78:81]
	s_add_i32 s36, s36, 2
	s_addk_i32 s10, 0x80
	v_lshl_add_u64 v[146:147], v[146:147], 0, s[14:15]
	s_waitcnt lgkmcnt(2)
	v_mfma_f32_16x16x32_bf16 v[74:77], v[210:213], v[166:169], v[74:77]
	s_and_b64 vcc, exec, s[0:1]
	v_mfma_f32_16x16x32_bf16 v[70:73], v[214:217], v[166:169], v[70:73]
	v_mfma_f32_16x16x32_bf16 v[62:65], v[218:221], v[166:169], v[62:65]
	v_exp_f32_e32 v167, v189
	v_exp_f32_e32 v169, v193
	v_cvt_pk_bf16_f32 v166, v186, v187
	s_waitcnt lgkmcnt(1)
	v_mfma_f32_16x16x32_bf16 v[202:205], v[170:173], v[34:37], v[2:5]
	v_cvt_pk_bf16_f32 v167, v229, v167
	v_exp_f32_e32 v229, v182
	v_exp_f32_e32 v182, v195
	v_exp_f32_e32 v195, v183
	v_exp_f32_e32 v183, v196
	v_exp_f32_e32 v196, v184
	v_exp_f32_e32 v184, v197
	v_cvt_pk_bf16_f32 v168, v190, v191
	v_cvt_pk_bf16_f32 v169, v192, v169
	v_cvt_pk_bf16_f32 v182, v194, v182
	v_cvt_pk_bf16_f32 v183, v183, v184
	v_cvt_pk_bf16_f32 v184, v229, v195
	v_cvt_pk_bf16_f32 v185, v196, v185
	v_mfma_f32_16x16x32_bf16 v[170:173], v[170:173], v[38:41], v[10:13]
	v_exp_f32_e32 v194, v198
	v_exp_f32_e32 v195, v202
	v_exp_f32_e32 v196, v199
	v_mfma_f32_16x16x32_bf16 v[122:125], v[178:181], v[174:177], v[122:125]
	v_exp_f32_e32 v198, v205
	v_exp_f32_e32 v197, v201
	v_mfma_f32_16x16x32_bf16 v[102:105], v[178:181], v[166:169], v[102:105]
	v_mfma_f32_16x16x32_bf16 v[58:61], v[178:181], v[182:185], v[58:61]
	v_exp_f32_e32 v180, v203
	v_exp_f32_e32 v181, v204
	v_exp_f32_e32 v179, v200
	v_mfma_f32_16x16x32_bf16 v[126:129], v[240:243], v[174:177], v[126:129]
	v_cvt_pk_bf16_f32 v178, v194, v196
	v_cvt_pk_bf16_f32 v180, v195, v180
	v_cvt_pk_bf16_f32 v181, v181, v198
	v_mfma_f32_16x16x32_bf16 v[118:121], v[210:213], v[174:177], v[118:121]
	v_exp_f32_e32 v194, v206
	v_exp_f32_e32 v195, v170
	v_exp_f32_e32 v170, v207
	v_mfma_f32_16x16x32_bf16 v[110:113], v[214:217], v[174:177], v[110:113]
	v_exp_f32_e32 v198, v172
	v_cvt_pk_bf16_f32 v179, v179, v197
	v_exp_f32_e32 v196, v171
	v_mfma_f32_16x16x32_bf16 v[106:109], v[218:221], v[174:177], v[106:109]
	ds_read_b128 v[174:177], v247 offset:6144
	v_exp_f32_e32 v197, v208
	ds_read_b128 v[202:205], v246 offset:14336
	v_mfma_f32_16x16x32_bf16 v[114:117], v[240:243], v[166:169], v[114:117]
	v_mfma_f32_16x16x32_bf16 v[98:101], v[210:213], v[166:169], v[98:101]
	v_mfma_f32_16x16x32_bf16 v[94:97], v[214:217], v[166:169], v[94:97]
	v_mfma_f32_16x16x32_bf16 v[90:93], v[218:221], v[166:169], v[90:93]
	v_exp_f32_e32 v169, v173
	v_exp_f32_e32 v167, v209
	v_cvt_pk_bf16_f32 v166, v194, v170
	v_mfma_f32_16x16x32_bf16 v[82:85], v[240:243], v[182:185], v[82:85]
	v_cvt_pk_bf16_f32 v169, v198, v169
	v_mfma_f32_16x16x32_bf16 v[54:57], v[210:213], v[182:185], v[54:57]
	ds_read_b64 v[170:171], v248 offset:64
	ds_read_b64 v[172:173], v248 offset:96
	v_cvt_pk_bf16_f32 v167, v197, v167
	v_mfma_f32_16x16x32_bf16 v[50:53], v[214:217], v[182:185], v[50:53]
	v_cvt_pk_bf16_f32 v168, v195, v196
	ds_read_b64 v[194:195], v248 offset:4672
	ds_read_b64 v[196:197], v248 offset:4704
	ds_read_b64 v[198:199], v248 offset:6976
	ds_read_b64 v[200:201], v248 offset:7008
	v_mfma_f32_16x16x32_bf16 v[66:69], v[218:221], v[182:185], v[66:69]
	ds_read_b64 v[182:183], v248 offset:2368
	ds_read_b64 v[184:185], v248 offset:2400
	s_waitcnt lgkmcnt(10)
	v_mfma_f32_16x16x32_bf16 v[186:189], v[222:225], v[42:45], v[6:9]
	ds_read_b64 v[214:215], v248 offset:13824
	ds_read_b64 v[216:217], v248 offset:13856
	s_waitcnt lgkmcnt(11)
	v_mfma_f32_16x16x32_bf16 v[190:193], v[174:177], v[42:45], v[6:9]
	ds_read_b64 v[218:219], v248 offset:16128
	ds_read_b64 v[220:221], v248 offset:16160
	s_nop 1
	v_exp_f32_e32 v186, v186
	v_exp_f32_e32 v187, v187
	v_mfma_f32_16x16x32_bf16 v[222:225], v[222:225], v[46:49], v[14:17]
	v_exp_f32_e32 v188, v188
	s_nop 0
	v_exp_f32_e32 v190, v190
	v_exp_f32_e32 v191, v191
	v_mfma_f32_16x16x32_bf16 v[174:177], v[174:177], v[46:49], v[14:17]
	v_exp_f32_e32 v189, v189
	v_exp_f32_e32 v192, v192
	v_exp_f32_e32 v193, v193
	v_mfma_f32_16x16x32_bf16 v[126:129], v[240:243], v[178:181], v[126:129]
	v_cvt_pk_bf16_f32 v186, v186, v187
	v_cvt_pk_bf16_f32 v187, v188, v189
	v_cvt_pk_bf16_f32 v188, v190, v191
	v_mfma_f32_16x16x32_bf16 v[86:89], v[240:243], v[166:169], v[86:89]
	v_exp_f32_e32 v190, v222
	v_exp_f32_e32 v174, v174
	v_exp_f32_e32 v191, v223
	s_waitcnt lgkmcnt(10)
	v_mfma_f32_16x16x32_bf16 v[122:125], v[170:173], v[178:181], v[122:125]
	v_exp_f32_e32 v175, v175
	v_exp_f32_e32 v176, v176
	v_cvt_pk_bf16_f32 v189, v192, v193
	v_mfma_f32_16x16x32_bf16 v[78:81], v[170:173], v[166:169], v[78:81]
	s_waitcnt lgkmcnt(4)
	v_mfma_f32_16x16x32_bf16 v[118:121], v[182:185], v[178:181], v[118:121]
	v_mfma_f32_16x16x32_bf16 v[74:77], v[182:185], v[166:169], v[74:77]
	v_mfma_f32_16x16x32_bf16 v[110:113], v[194:197], v[178:181], v[110:113]
	v_mfma_f32_16x16x32_bf16 v[70:73], v[194:197], v[166:169], v[70:73]
	v_mfma_f32_16x16x32_bf16 v[106:109], v[198:201], v[178:181], v[106:109]
	v_exp_f32_e32 v178, v224
	v_mfma_f32_16x16x32_bf16 v[62:65], v[198:201], v[166:169], v[62:65]
	v_exp_f32_e32 v167, v225
	v_exp_f32_e32 v169, v177
	v_cvt_pk_bf16_f32 v166, v190, v191
	v_cvt_pk_bf16_f32 v168, v174, v175
	v_cvt_pk_bf16_f32 v167, v178, v167
	v_cvt_pk_bf16_f32 v169, v176, v169
	v_mfma_f32_16x16x32_bf16 v[102:105], v[170:173], v[186:189], v[102:105]
	ds_read_b128 v[222:225], v247 offset:12288
	v_mfma_f32_16x16x32_bf16 v[82:85], v[240:243], v[166:169], v[82:85]
	v_mfma_f32_16x16x32_bf16 v[58:61], v[170:173], v[166:169], v[58:61]
	ds_read_b128 v[170:173], v246 offset:8192
	v_mfma_f32_16x16x32_bf16 v[54:57], v[182:185], v[166:169], v[54:57]
	v_mfma_f32_16x16x32_bf16 v[50:53], v[194:197], v[166:169], v[50:53]
	v_mfma_f32_16x16x32_bf16 v[66:69], v[198:201], v[166:169], v[66:69]
	ds_read_b128 v[166:169], v246 offset:10240
	s_waitcnt lgkmcnt(1)
	v_mfma_f32_16x16x32_bf16 v[174:177], v[170:173], v[34:37], v[2:5]
	s_waitcnt lgkmcnt(0)
	v_mfma_f32_16x16x32_bf16 v[178:181], v[166:169], v[34:37], v[2:5]
	s_nop 5
	v_exp_f32_e32 v174, v174
	v_mfma_f32_16x16x32_bf16 v[170:173], v[170:173], v[38:41], v[10:13]
	v_exp_f32_e32 v206, v178
	v_exp_f32_e32 v175, v175
	v_exp_f32_e32 v207, v179
	v_mfma_f32_16x16x32_bf16 v[166:169], v[166:169], v[38:41], v[10:13]
	v_exp_f32_e32 v176, v176
	s_nop 2
	v_exp_f32_e32 v170, v170
	v_exp_f32_e32 v208, v180
	v_mfma_f32_16x16x32_bf16 v[114:117], v[240:243], v[186:189], v[114:117]
	v_exp_f32_e32 v177, v177
	v_exp_f32_e32 v211, v166
	v_exp_f32_e32 v166, v171
	v_exp_f32_e32 v171, v167
	v_exp_f32_e32 v167, v172
	v_exp_f32_e32 v172, v168
	v_exp_f32_e32 v168, v173
	v_exp_f32_e32 v169, v169
	v_mfma_f32_16x16x32_bf16 v[98:101], v[182:185], v[186:189], v[98:101]
	ds_read_b128 v[182:185], v247 offset:8192
	v_cvt_pk_bf16_f32 v166, v170, v166
	v_cvt_pk_bf16_f32 v167, v167, v168
	v_mfma_f32_16x16x32_bf16 v[94:97], v[194:197], v[186:189], v[94:97]
	v_cvt_pk_bf16_f32 v168, v211, v171
	v_cvt_pk_bf16_f32 v169, v172, v169
	ds_read_b64 v[170:171], v248 offset:9216
	ds_read_b64 v[172:173], v248 offset:9248
	v_mfma_f32_16x16x32_bf16 v[90:93], v[198:201], v[186:189], v[90:93]
	ds_read_b128 v[186:189], v247 offset:10240
	ds_read_b64 v[210:211], v248 offset:11520
	ds_read_b64 v[212:213], v248 offset:11552
	ds_read_b128 v[198:201], v246 offset:12288
	s_waitcnt lgkmcnt(6)
	v_mfma_f32_16x16x32_bf16 v[190:193], v[182:185], v[42:45], v[6:9]
	v_exp_f32_e32 v209, v181
	v_cvt_pk_bf16_f32 v174, v174, v175
	v_cvt_pk_bf16_f32 v175, v176, v177
	s_waitcnt lgkmcnt(3)
	v_mfma_f32_16x16x32_bf16 v[194:197], v[186:189], v[42:45], v[6:9]
	v_cvt_pk_bf16_f32 v176, v206, v207
	s_nop 1
	v_exp_f32_e32 v190, v190
	v_exp_f32_e32 v191, v191
	v_mfma_f32_16x16x32_bf16 v[182:185], v[182:185], v[46:49], v[14:17]
	s_nop 1
	v_exp_f32_e32 v194, v194
	v_exp_f32_e32 v195, v195
	v_exp_f32_e32 v226, v192
	v_mfma_f32_16x16x32_bf16 v[186:189], v[186:189], v[46:49], v[14:17]
	v_exp_f32_e32 v196, v196
	s_nop 0
	v_exp_f32_e32 v182, v182
	v_exp_f32_e32 v183, v183
	v_mfma_f32_16x16x32_bf16 v[86:89], v[240:243], v[166:169], v[86:89]
	v_exp_f32_e32 v184, v184
	s_nop 1
	v_exp_f32_e32 v186, v186
	v_exp_f32_e32 v187, v187
	v_mfma_f32_16x16x32_bf16 v[78:81], v[170:173], v[166:169], v[78:81]
	v_exp_f32_e32 v188, v188
	v_exp_f32_e32 v185, v185
	v_exp_f32_e32 v189, v189
	s_waitcnt lgkmcnt(1)
	v_mfma_f32_16x16x32_bf16 v[74:77], v[210:213], v[166:169], v[74:77]
	v_cvt_pk_bf16_f32 v177, v208, v209
	v_cvt_pk_bf16_f32 v182, v182, v183
	v_cvt_pk_bf16_f32 v183, v184, v185
	v_mfma_f32_16x16x32_bf16 v[70:73], v[214:217], v[166:169], v[70:73]
	v_cvt_pk_bf16_f32 v184, v186, v187
	v_cvt_pk_bf16_f32 v185, v188, v189
	v_mfma_f32_16x16x32_bf16 v[62:65], v[218:221], v[166:169], v[62:65]
	v_exp_f32_e32 v167, v193
	v_exp_f32_e32 v169, v197
	v_cvt_pk_bf16_f32 v166, v190, v191
	s_waitcnt lgkmcnt(0)
	v_mfma_f32_16x16x32_bf16 v[178:181], v[198:201], v[34:37], v[2:5]
	v_cvt_pk_bf16_f32 v167, v226, v167
	v_cvt_pk_bf16_f32 v168, v194, v195
	v_cvt_pk_bf16_f32 v169, v196, v169
	v_mfma_f32_16x16x32_bf16 v[206:209], v[202:205], v[34:37], v[2:5]
	v_mfma_f32_16x16x32_bf16 v[198:201], v[198:201], v[38:41], v[10:13]
	s_nop 2
	v_exp_f32_e32 v178, v178
	s_nop 2
	v_exp_f32_e32 v186, v206
	v_mfma_f32_16x16x32_bf16 v[202:205], v[202:205], v[38:41], v[10:13]
	v_mfma_f32_16x16x32_bf16 v[122:125], v[170:173], v[174:177], v[122:125]
	v_exp_f32_e32 v188, v200
	s_nop 5
	v_exp_f32_e32 v187, v203
	v_exp_f32_e32 v189, v205
	v_mfma_f32_16x16x32_bf16 v[102:105], v[170:173], v[166:169], v[102:105]
	v_mfma_f32_16x16x32_bf16 v[58:61], v[170:173], v[182:185], v[58:61]
	v_exp_f32_e32 v170, v179
	v_exp_f32_e32 v172, v207
	v_exp_f32_e32 v171, v180
	v_exp_f32_e32 v179, v181
	v_mfma_f32_16x16x32_bf16 v[126:129], v[240:243], v[174:177], v[126:129]
	v_exp_f32_e32 v173, v208
	v_exp_f32_e32 v180, v209
	v_cvt_pk_bf16_f32 v170, v178, v170
	v_mfma_f32_16x16x32_bf16 v[118:121], v[210:213], v[174:177], v[118:121]
	v_cvt_pk_bf16_f32 v171, v171, v179
	v_cvt_pk_bf16_f32 v172, v186, v172
	v_exp_f32_e32 v178, v198
	v_mfma_f32_16x16x32_bf16 v[110:113], v[214:217], v[174:177], v[110:113]
	v_exp_f32_e32 v186, v202
	v_exp_f32_e32 v179, v199
	v_cvt_pk_bf16_f32 v173, v173, v180
	v_mfma_f32_16x16x32_bf16 v[106:109], v[218:221], v[174:177], v[106:109]
	ds_read_b128 v[174:177], v247 offset:14336
	v_mfma_f32_16x16x32_bf16 v[114:117], v[240:243], v[166:169], v[114:117]
	v_mfma_f32_16x16x32_bf16 v[98:101], v[210:213], v[166:169], v[98:101]
	v_mfma_f32_16x16x32_bf16 v[94:97], v[214:217], v[166:169], v[94:97]
	v_mfma_f32_16x16x32_bf16 v[90:93], v[218:221], v[166:169], v[90:93]
	v_exp_f32_e32 v169, v204
	v_exp_f32_e32 v167, v201
	v_mfma_f32_16x16x32_bf16 v[82:85], v[240:243], v[182:185], v[82:85]
	v_cvt_pk_bf16_f32 v166, v178, v179
	ds_read_b64 v[178:179], v248 offset:9280
	ds_read_b64 v[180:181], v248 offset:9312
	v_cvt_pk_bf16_f32 v168, v186, v187
	v_mfma_f32_16x16x32_bf16 v[54:57], v[210:213], v[182:185], v[54:57]
	v_cvt_pk_bf16_f32 v167, v188, v167
	v_cvt_pk_bf16_f32 v169, v169, v189
	v_mfma_f32_16x16x32_bf16 v[50:53], v[214:217], v[182:185], v[50:53]
	ds_read_b64 v[186:187], v248 offset:13888
	ds_read_b64 v[188:189], v248 offset:13920
	ds_read_b64 v[198:199], v248 offset:16192
	ds_read_b64 v[200:201], v248 offset:16224
	v_mfma_f32_16x16x32_bf16 v[66:69], v[218:221], v[182:185], v[66:69]
	ds_read_b64 v[182:183], v248 offset:11584
	ds_read_b64 v[184:185], v248 offset:11616
	v_mfma_f32_16x16x32_bf16 v[190:193], v[222:225], v[42:45], v[6:9]
	s_waitcnt lgkmcnt(8)
	v_mfma_f32_16x16x32_bf16 v[194:197], v[174:177], v[42:45], v[6:9]
	v_mfma_f32_16x16x32_bf16 v[222:225], v[222:225], v[46:49], v[14:17]
	s_nop 4
	v_exp_f32_e32 v190, v190
	s_nop 0
	v_exp_f32_e32 v194, v194
	v_exp_f32_e32 v191, v191
	v_mfma_f32_16x16x32_bf16 v[174:177], v[174:177], v[46:49], v[14:17]
	v_exp_f32_e32 v195, v195
	v_exp_f32_e32 v192, v192
	v_exp_f32_e32 v193, v193
	v_mfma_f32_16x16x32_bf16 v[126:129], v[240:243], v[170:173], v[126:129]
	v_exp_f32_e32 v196, v196
	v_exp_f32_e32 v197, v197
	v_cvt_pk_bf16_f32 v190, v190, v191
	v_mfma_f32_16x16x32_bf16 v[86:89], v[240:243], v[166:169], v[86:89]
	v_cvt_pk_bf16_f32 v191, v192, v193
	v_cvt_pk_bf16_f32 v192, v194, v195
	v_exp_f32_e32 v194, v222
	s_waitcnt lgkmcnt(6)
	v_mfma_f32_16x16x32_bf16 v[122:125], v[178:181], v[170:173], v[122:125]
	v_exp_f32_e32 v174, v174
	v_exp_f32_e32 v195, v223
	v_cvt_pk_bf16_f32 v193, v196, v197
	v_mfma_f32_16x16x32_bf16 v[78:81], v[178:181], v[166:169], v[78:81]
	s_waitcnt lgkmcnt(0)
	v_mfma_f32_16x16x32_bf16 v[118:121], v[182:185], v[170:173], v[118:121]
	v_mfma_f32_16x16x32_bf16 v[74:77], v[182:185], v[166:169], v[74:77]
	v_mfma_f32_16x16x32_bf16 v[110:113], v[186:189], v[170:173], v[110:113]
	v_mfma_f32_16x16x32_bf16 v[70:73], v[186:189], v[166:169], v[70:73]
	v_mfma_f32_16x16x32_bf16 v[106:109], v[198:201], v[170:173], v[106:109]
	v_exp_f32_e32 v170, v175
	v_exp_f32_e32 v171, v224
	v_exp_f32_e32 v172, v176
	v_mfma_f32_16x16x32_bf16 v[62:65], v[198:201], v[166:169], v[62:65]
	v_exp_f32_e32 v167, v225
	v_exp_f32_e32 v169, v177
	v_cvt_pk_bf16_f32 v166, v194, v195
	v_cvt_pk_bf16_f32 v168, v174, v170
	v_cvt_pk_bf16_f32 v167, v171, v167
	v_cvt_pk_bf16_f32 v169, v172, v169
	v_mfma_f32_16x16x32_bf16 v[114:117], v[240:243], v[190:193], v[114:117]
	s_nop 0
	v_mfma_f32_16x16x32_bf16 v[82:85], v[240:243], v[166:169], v[82:85]
	v_mfma_f32_16x16x32_bf16 v[102:105], v[178:181], v[190:193], v[102:105]
	v_mfma_f32_16x16x32_bf16 v[58:61], v[178:181], v[166:169], v[58:61]
	v_mfma_f32_16x16x32_bf16 v[98:101], v[182:185], v[190:193], v[98:101]
	v_mfma_f32_16x16x32_bf16 v[54:57], v[182:185], v[166:169], v[54:57]
	v_mfma_f32_16x16x32_bf16 v[94:97], v[186:189], v[190:193], v[94:97]
	v_mfma_f32_16x16x32_bf16 v[50:53], v[186:189], v[166:169], v[50:53]
	v_mfma_f32_16x16x32_bf16 v[90:93], v[198:201], v[190:193], v[90:93]
	v_mfma_f32_16x16x32_bf16 v[66:69], v[198:201], v[166:169], v[66:69]
	s_cbranch_vccnz .LBB0_2162
.Ldiff_hB_2159:
	s_and_b32 s0, s10, 0x80
	s_lshl_b32 s1, s0, 7
	s_add_i32 s37, s1, 0
	s_lshl_b32 s0, s0, 4
	s_add_i32 s2, s37, s0
	s_cmpk_gt_u32 s36, 0x101
	s_cselect_b64 s[0:1], -1, 0
	s_and_b64 vcc, exec, s[0:1]
	s_waitcnt vmcnt(3)
	ds_write_b128 v244, v[18:21] offset:16384
	s_waitcnt vmcnt(1)
	ds_write_b128 v245, v[22:25] offset:18432
	s_waitcnt vmcnt(1)
	ds_write_b128 v244, v[26:29] offset:24576
	s_waitcnt vmcnt(0)
	ds_write_b128 v245, v[30:33] offset:27648
	s_waitcnt lgkmcnt(0)
	s_barrier
	ds_read_b128 v[130:133], v246 offset:16384
	ds_read_b128 v[166:169], v246 offset:18432
	s_cbranch_vccnz .Ldiff_bB_2159
	s_cmp_eq_u32 s10, 0
	s_cbranch_scc0 .Lpf_nextB_2159
	v_add_u32_e32 v250, s34, v159
	v_mad_i64_i32 v[250:251], s[38:39], v250, s19, v[144:145]
	v_add_u32_e32 v252, s35, v159
	v_mad_i64_i32 v[252:253], s[38:39], v252, s19, v[144:145]
	s_sub_i32 s100, s33, s34
	s_mul_hi_i32 s101, s100, 0x1640
	s_mul_i32 s100, s100, 0x1640
	s_branch .Lpf_loadB_2159

.Ldiff_bB_2159:
	s_waitcnt lgkmcnt(1)
	v_mfma_f32_16x16x32_bf16 v[170:173], v[130:133], v[34:37], v[2:5]
	ds_read_b128 v[182:185], v247 offset:18432
	v_mfma_f32_16x16x32_bf16 v[178:181], v[130:133], v[38:41], v[10:13]
	ds_read_b128 v[130:133], v247 offset:16384
	s_nop 2
	s_nop 1
	v_exp_f32_e32 v198, v170
	v_exp_f32_e32 v199, v173
	s_waitcnt lgkmcnt(2)
	v_mfma_f32_16x16x32_bf16 v[174:177], v[166:169], v[34:37], v[2:5]
	v_exp_f32_e32 v178, v178
	ds_read_b64 v[214:215], v248 offset:23040
	ds_read_b64 v[216:217], v248 offset:23072
	v_mfma_f32_16x16x32_bf16 v[166:169], v[166:169], v[38:41], v[10:13]
	ds_read_b64 v[218:219], v248 offset:25344
	ds_read_b64 v[220:221], v248 offset:25376
	s_nop 2
	v_exp_f32_e32 v202, v174
	v_exp_f32_e32 v174, v171
	s_waitcnt lgkmcnt(4)
	v_mfma_f32_16x16x32_bf16 v[186:189], v[130:133], v[42:45], v[6:9]
	v_exp_f32_e32 v203, v175
	v_exp_f32_e32 v211, v166
	v_exp_f32_e32 v166, v179
	v_mfma_f32_16x16x32_bf16 v[194:197], v[130:133], v[46:49], v[14:17]
	ds_read_b128 v[130:133], v246 offset:20480
	v_exp_f32_e32 v179, v167
	v_exp_f32_e32 v167, v180
	v_exp_f32_e32 v180, v168
	v_exp_f32_e32 v168, v181
	v_exp_f32_e32 v169, v169
	v_exp_f32_e32 v175, v172
	v_cvt_pk_bf16_f32 v166, v178, v166
	v_cvt_pk_bf16_f32 v167, v167, v168
	v_cvt_pk_bf16_f32 v168, v211, v179
	v_cvt_pk_bf16_f32 v169, v180, v169
	ds_read_b64 v[178:179], v248 offset:18432
	ds_read_b64 v[180:181], v248 offset:18464
	ds_read_b64 v[210:211], v248 offset:20736
	ds_read_b64 v[212:213], v248 offset:20768
	ds_read_b128 v[170:173], v246 offset:22528
	v_cvt_pk_bf16_f32 v174, v198, v174
	v_cvt_pk_bf16_f32 v175, v175, v199
	s_waitcnt lgkmcnt(5)
	v_mfma_f32_16x16x32_bf16 v[198:201], v[130:133], v[34:37], v[2:5]
	v_exp_f32_e32 v229, v188
	v_exp_f32_e32 v204, v176
	v_exp_f32_e32 v177, v177
	v_mfma_f32_16x16x32_bf16 v[206:209], v[130:133], v[38:41], v[10:13]
	v_exp_f32_e32 v186, v186
	v_mfma_f32_16x16x32_bf16 v[190:193], v[182:185], v[42:45], v[6:9]
	v_exp_f32_e32 v187, v187
	v_exp_f32_e32 v194, v194
	v_cvt_pk_bf16_f32 v176, v202, v203
	v_mfma_f32_16x16x32_bf16 v[182:185], v[182:185], v[46:49], v[14:17]
	v_cvt_pk_bf16_f32 v177, v204, v177
	s_nop 2
	v_exp_f32_e32 v190, v190
	v_exp_f32_e32 v191, v191
	v_mfma_f32_16x16x32_bf16 v[86:89], v[240:243], v[166:169], v[86:89]
	v_exp_f32_e32 v192, v192
	v_exp_f32_e32 v185, v185
	ds_read_b128 v[222:225], v247 offset:20480
	s_waitcnt lgkmcnt(4)
	v_mfma_f32_16x16x32_bf16 v[78:81], v[178:181], v[166:169], v[78:81]
	s_add_i32 s36, s36, 2
	s_addk_i32 s10, 0x80
	v_lshl_add_u64 v[146:147], v[146:147], 0, s[14:15]
	s_waitcnt lgkmcnt(2)
	v_mfma_f32_16x16x32_bf16 v[74:77], v[210:213], v[166:169], v[74:77]
	s_and_b64 vcc, exec, s[0:1]
	v_mfma_f32_16x16x32_bf16 v[70:73], v[214:217], v[166:169], v[70:73]
	v_mfma_f32_16x16x32_bf16 v[62:65], v[218:221], v[166:169], v[62:65]
	v_exp_f32_e32 v167, v189
	v_exp_f32_e32 v169, v193
	v_cvt_pk_bf16_f32 v166, v186, v187
	s_waitcnt lgkmcnt(1)
	v_mfma_f32_16x16x32_bf16 v[202:205], v[170:173], v[34:37], v[2:5]
	v_cvt_pk_bf16_f32 v167, v229, v167
	v_exp_f32_e32 v229, v182
	v_exp_f32_e32 v182, v195
	v_exp_f32_e32 v195, v183
	v_exp_f32_e32 v183, v196
	v_exp_f32_e32 v196, v184
	v_exp_f32_e32 v184, v197
	v_cvt_pk_bf16_f32 v168, v190, v191
	v_cvt_pk_bf16_f32 v169, v192, v169
	v_cvt_pk_bf16_f32 v182, v194, v182
	v_cvt_pk_bf16_f32 v183, v183, v184
	v_cvt_pk_bf16_f32 v184, v229, v195
	v_cvt_pk_bf16_f32 v185, v196, v185
	v_mfma_f32_16x16x32_bf16 v[170:173], v[170:173], v[38:41], v[10:13]
	v_exp_f32_e32 v194, v198
	v_exp_f32_e32 v195, v202
	v_exp_f32_e32 v196, v199
	v_mfma_f32_16x16x32_bf16 v[122:125], v[178:181], v[174:177], v[122:125]
	v_exp_f32_e32 v198, v205
	v_exp_f32_e32 v197, v201
	v_mfma_f32_16x16x32_bf16 v[102:105], v[178:181], v[166:169], v[102:105]
	v_mfma_f32_16x16x32_bf16 v[58:61], v[178:181], v[182:185], v[58:61]
	v_exp_f32_e32 v180, v203
	v_exp_f32_e32 v181, v204
	v_exp_f32_e32 v179, v200
	v_mfma_f32_16x16x32_bf16 v[126:129], v[240:243], v[174:177], v[126:129]
	v_cvt_pk_bf16_f32 v178, v194, v196
	v_cvt_pk_bf16_f32 v180, v195, v180
	v_cvt_pk_bf16_f32 v181, v181, v198
	v_mfma_f32_16x16x32_bf16 v[118:121], v[210:213], v[174:177], v[118:121]
	v_exp_f32_e32 v194, v206
	v_exp_f32_e32 v195, v170
	v_exp_f32_e32 v170, v207
	v_mfma_f32_16x16x32_bf16 v[110:113], v[214:217], v[174:177], v[110:113]
	v_exp_f32_e32 v198, v172
	v_cvt_pk_bf16_f32 v179, v179, v197
	v_exp_f32_e32 v196, v171
	v_mfma_f32_16x16x32_bf16 v[106:109], v[218:221], v[174:177], v[106:109]
	ds_read_b128 v[174:177], v247 offset:22528
	v_exp_f32_e32 v197, v208
	ds_read_b128 v[202:205], v246 offset:30720
	v_mfma_f32_16x16x32_bf16 v[114:117], v[240:243], v[166:169], v[114:117]
	v_mfma_f32_16x16x32_bf16 v[98:101], v[210:213], v[166:169], v[98:101]
	v_mfma_f32_16x16x32_bf16 v[94:97], v[214:217], v[166:169], v[94:97]
	v_mfma_f32_16x16x32_bf16 v[90:93], v[218:221], v[166:169], v[90:93]
	v_exp_f32_e32 v169, v173
	v_exp_f32_e32 v167, v209
	v_cvt_pk_bf16_f32 v166, v194, v170
	v_mfma_f32_16x16x32_bf16 v[82:85], v[240:243], v[182:185], v[82:85]
	v_cvt_pk_bf16_f32 v169, v198, v169
	v_mfma_f32_16x16x32_bf16 v[54:57], v[210:213], v[182:185], v[54:57]
	ds_read_b64 v[170:171], v248 offset:18496
	ds_read_b64 v[172:173], v248 offset:18528
	v_cvt_pk_bf16_f32 v167, v197, v167
	v_mfma_f32_16x16x32_bf16 v[50:53], v[214:217], v[182:185], v[50:53]
	v_cvt_pk_bf16_f32 v168, v195, v196
	ds_read_b64 v[194:195], v248 offset:23104
	ds_read_b64 v[196:197], v248 offset:23136
	ds_read_b64 v[198:199], v248 offset:25408
	ds_read_b64 v[200:201], v248 offset:25440
	v_mfma_f32_16x16x32_bf16 v[66:69], v[218:221], v[182:185], v[66:69]
	ds_read_b64 v[182:183], v248 offset:20800
	ds_read_b64 v[184:185], v248 offset:20832
	s_waitcnt lgkmcnt(10)
	v_mfma_f32_16x16x32_bf16 v[186:189], v[222:225], v[42:45], v[6:9]
	ds_read_b64 v[214:215], v248 offset:32256
	ds_read_b64 v[216:217], v248 offset:32288
	s_waitcnt lgkmcnt(11)
	v_mfma_f32_16x16x32_bf16 v[190:193], v[174:177], v[42:45], v[6:9]
	ds_read_b64 v[218:219], v248 offset:34560
	ds_read_b64 v[220:221], v248 offset:34592
	s_nop 1
	v_exp_f32_e32 v186, v186
	v_exp_f32_e32 v187, v187
	v_mfma_f32_16x16x32_bf16 v[222:225], v[222:225], v[46:49], v[14:17]
	v_exp_f32_e32 v188, v188
	s_nop 0
	v_exp_f32_e32 v190, v190
	v_exp_f32_e32 v191, v191
	v_mfma_f32_16x16x32_bf16 v[174:177], v[174:177], v[46:49], v[14:17]
	v_exp_f32_e32 v189, v189
	v_exp_f32_e32 v192, v192
	v_exp_f32_e32 v193, v193
	v_mfma_f32_16x16x32_bf16 v[126:129], v[240:243], v[178:181], v[126:129]
	v_cvt_pk_bf16_f32 v186, v186, v187
	v_cvt_pk_bf16_f32 v187, v188, v189
	v_cvt_pk_bf16_f32 v188, v190, v191
	v_mfma_f32_16x16x32_bf16 v[86:89], v[240:243], v[166:169], v[86:89]
	v_exp_f32_e32 v190, v222
	v_exp_f32_e32 v174, v174
	v_exp_f32_e32 v191, v223
	s_waitcnt lgkmcnt(10)
	v_mfma_f32_16x16x32_bf16 v[122:125], v[170:173], v[178:181], v[122:125]
	v_exp_f32_e32 v175, v175
	v_exp_f32_e32 v176, v176
	v_cvt_pk_bf16_f32 v189, v192, v193
	v_mfma_f32_16x16x32_bf16 v[78:81], v[170:173], v[166:169], v[78:81]
	s_waitcnt lgkmcnt(4)
	v_mfma_f32_16x16x32_bf16 v[118:121], v[182:185], v[178:181], v[118:121]
	v_mfma_f32_16x16x32_bf16 v[74:77], v[182:185], v[166:169], v[74:77]
	v_mfma_f32_16x16x32_bf16 v[110:113], v[194:197], v[178:181], v[110:113]
	v_mfma_f32_16x16x32_bf16 v[70:73], v[194:197], v[166:169], v[70:73]
	v_mfma_f32_16x16x32_bf16 v[106:109], v[198:201], v[178:181], v[106:109]
	v_exp_f32_e32 v178, v224
	v_mfma_f32_16x16x32_bf16 v[62:65], v[198:201], v[166:169], v[62:65]
	v_exp_f32_e32 v167, v225
	v_exp_f32_e32 v169, v177
	v_cvt_pk_bf16_f32 v166, v190, v191
	v_cvt_pk_bf16_f32 v168, v174, v175
	v_cvt_pk_bf16_f32 v167, v178, v167
	v_cvt_pk_bf16_f32 v169, v176, v169
	v_mfma_f32_16x16x32_bf16 v[102:105], v[170:173], v[186:189], v[102:105]
	ds_read_b128 v[222:225], v247 offset:28672
	v_mfma_f32_16x16x32_bf16 v[82:85], v[240:243], v[166:169], v[82:85]
	v_mfma_f32_16x16x32_bf16 v[58:61], v[170:173], v[166:169], v[58:61]
	ds_read_b128 v[170:173], v246 offset:24576
	v_mfma_f32_16x16x32_bf16 v[54:57], v[182:185], v[166:169], v[54:57]
	v_mfma_f32_16x16x32_bf16 v[50:53], v[194:197], v[166:169], v[50:53]
	v_mfma_f32_16x16x32_bf16 v[66:69], v[198:201], v[166:169], v[66:69]
	ds_read_b128 v[166:169], v246 offset:26624
	s_waitcnt lgkmcnt(1)
	v_mfma_f32_16x16x32_bf16 v[174:177], v[170:173], v[34:37], v[2:5]
	s_waitcnt lgkmcnt(0)
	v_mfma_f32_16x16x32_bf16 v[178:181], v[166:169], v[34:37], v[2:5]
	s_nop 5
	v_exp_f32_e32 v174, v174
	v_mfma_f32_16x16x32_bf16 v[170:173], v[170:173], v[38:41], v[10:13]
	v_exp_f32_e32 v206, v178
	v_exp_f32_e32 v175, v175
	v_exp_f32_e32 v207, v179
	v_mfma_f32_16x16x32_bf16 v[166:169], v[166:169], v[38:41], v[10:13]
	v_exp_f32_e32 v176, v176
	s_nop 2
	v_exp_f32_e32 v170, v170
	v_exp_f32_e32 v208, v180
	v_mfma_f32_16x16x32_bf16 v[114:117], v[240:243], v[186:189], v[114:117]
	v_exp_f32_e32 v177, v177
	v_exp_f32_e32 v211, v166
	v_exp_f32_e32 v166, v171
	v_exp_f32_e32 v171, v167
	v_exp_f32_e32 v167, v172
	v_exp_f32_e32 v172, v168
	v_exp_f32_e32 v168, v173
	v_exp_f32_e32 v169, v169
	v_mfma_f32_16x16x32_bf16 v[98:101], v[182:185], v[186:189], v[98:101]
	ds_read_b128 v[182:185], v247 offset:24576
	v_cvt_pk_bf16_f32 v166, v170, v166
	v_cvt_pk_bf16_f32 v167, v167, v168
	v_mfma_f32_16x16x32_bf16 v[94:97], v[194:197], v[186:189], v[94:97]
	v_cvt_pk_bf16_f32 v168, v211, v171
	v_cvt_pk_bf16_f32 v169, v172, v169
	ds_read_b64 v[170:171], v248 offset:27648
	ds_read_b64 v[172:173], v248 offset:27680
	v_mfma_f32_16x16x32_bf16 v[90:93], v[198:201], v[186:189], v[90:93]
	ds_read_b128 v[186:189], v247 offset:26624
	ds_read_b64 v[210:211], v248 offset:29952
	ds_read_b64 v[212:213], v248 offset:29984
	ds_read_b128 v[198:201], v246 offset:28672
	s_waitcnt lgkmcnt(6)
	v_mfma_f32_16x16x32_bf16 v[190:193], v[182:185], v[42:45], v[6:9]
	v_exp_f32_e32 v209, v181
	v_cvt_pk_bf16_f32 v174, v174, v175
	v_cvt_pk_bf16_f32 v175, v176, v177
	s_waitcnt lgkmcnt(3)
	v_mfma_f32_16x16x32_bf16 v[194:197], v[186:189], v[42:45], v[6:9]
	v_cvt_pk_bf16_f32 v176, v206, v207
	s_nop 1
	v_exp_f32_e32 v190, v190
	v_exp_f32_e32 v191, v191
	v_mfma_f32_16x16x32_bf16 v[182:185], v[182:185], v[46:49], v[14:17]
	s_nop 1
	v_exp_f32_e32 v194, v194
	v_exp_f32_e32 v195, v195
	v_exp_f32_e32 v226, v192
	v_mfma_f32_16x16x32_bf16 v[186:189], v[186:189], v[46:49], v[14:17]
	v_exp_f32_e32 v196, v196
	s_nop 0
	v_exp_f32_e32 v182, v182
	v_exp_f32_e32 v183, v183
	v_mfma_f32_16x16x32_bf16 v[86:89], v[240:243], v[166:169], v[86:89]
	v_exp_f32_e32 v184, v184
	s_nop 1
	v_exp_f32_e32 v186, v186
	v_exp_f32_e32 v187, v187
	v_mfma_f32_16x16x32_bf16 v[78:81], v[170:173], v[166:169], v[78:81]
	v_exp_f32_e32 v188, v188
	v_exp_f32_e32 v185, v185
	v_exp_f32_e32 v189, v189
	s_waitcnt lgkmcnt(1)
	v_mfma_f32_16x16x32_bf16 v[74:77], v[210:213], v[166:169], v[74:77]
	v_cvt_pk_bf16_f32 v177, v208, v209
	v_cvt_pk_bf16_f32 v182, v182, v183
	v_cvt_pk_bf16_f32 v183, v184, v185
	v_mfma_f32_16x16x32_bf16 v[70:73], v[214:217], v[166:169], v[70:73]
	v_cvt_pk_bf16_f32 v184, v186, v187
	v_cvt_pk_bf16_f32 v185, v188, v189
	v_mfma_f32_16x16x32_bf16 v[62:65], v[218:221], v[166:169], v[62:65]
	v_exp_f32_e32 v167, v193
	v_exp_f32_e32 v169, v197
	v_cvt_pk_bf16_f32 v166, v190, v191
	s_waitcnt lgkmcnt(0)
	v_mfma_f32_16x16x32_bf16 v[178:181], v[198:201], v[34:37], v[2:5]
	v_cvt_pk_bf16_f32 v167, v226, v167
	v_cvt_pk_bf16_f32 v168, v194, v195
	v_cvt_pk_bf16_f32 v169, v196, v169
	v_mfma_f32_16x16x32_bf16 v[206:209], v[202:205], v[34:37], v[2:5]
	v_mfma_f32_16x16x32_bf16 v[198:201], v[198:201], v[38:41], v[10:13]
	s_nop 2
	v_exp_f32_e32 v178, v178
	s_nop 2
	v_exp_f32_e32 v186, v206
	v_mfma_f32_16x16x32_bf16 v[202:205], v[202:205], v[38:41], v[10:13]
	v_mfma_f32_16x16x32_bf16 v[122:125], v[170:173], v[174:177], v[122:125]
	v_exp_f32_e32 v188, v200
	s_nop 5
	v_exp_f32_e32 v187, v203
	v_exp_f32_e32 v189, v205
	v_mfma_f32_16x16x32_bf16 v[102:105], v[170:173], v[166:169], v[102:105]
	v_mfma_f32_16x16x32_bf16 v[58:61], v[170:173], v[182:185], v[58:61]
	v_exp_f32_e32 v170, v179
	v_exp_f32_e32 v172, v207
	v_exp_f32_e32 v171, v180
	v_exp_f32_e32 v179, v181
	v_mfma_f32_16x16x32_bf16 v[126:129], v[240:243], v[174:177], v[126:129]
	v_exp_f32_e32 v173, v208
	v_exp_f32_e32 v180, v209
	v_cvt_pk_bf16_f32 v170, v178, v170
	v_mfma_f32_16x16x32_bf16 v[118:121], v[210:213], v[174:177], v[118:121]
	v_cvt_pk_bf16_f32 v171, v171, v179
	v_cvt_pk_bf16_f32 v172, v186, v172
	v_exp_f32_e32 v178, v198
	v_mfma_f32_16x16x32_bf16 v[110:113], v[214:217], v[174:177], v[110:113]
	v_exp_f32_e32 v186, v202
	v_exp_f32_e32 v179, v199
	v_cvt_pk_bf16_f32 v173, v173, v180
	v_mfma_f32_16x16x32_bf16 v[106:109], v[218:221], v[174:177], v[106:109]
	ds_read_b128 v[174:177], v247 offset:30720
	v_mfma_f32_16x16x32_bf16 v[114:117], v[240:243], v[166:169], v[114:117]
	v_mfma_f32_16x16x32_bf16 v[98:101], v[210:213], v[166:169], v[98:101]
	v_mfma_f32_16x16x32_bf16 v[94:97], v[214:217], v[166:169], v[94:97]
	v_mfma_f32_16x16x32_bf16 v[90:93], v[218:221], v[166:169], v[90:93]
	v_exp_f32_e32 v169, v204
	v_exp_f32_e32 v167, v201
	v_mfma_f32_16x16x32_bf16 v[82:85], v[240:243], v[182:185], v[82:85]
	v_cvt_pk_bf16_f32 v166, v178, v179
	ds_read_b64 v[178:179], v248 offset:27712
	ds_read_b64 v[180:181], v248 offset:27744
	v_cvt_pk_bf16_f32 v168, v186, v187
	v_mfma_f32_16x16x32_bf16 v[54:57], v[210:213], v[182:185], v[54:57]
	v_cvt_pk_bf16_f32 v167, v188, v167
	v_cvt_pk_bf16_f32 v169, v169, v189
	v_mfma_f32_16x16x32_bf16 v[50:53], v[214:217], v[182:185], v[50:53]
	ds_read_b64 v[186:187], v248 offset:32320
	ds_read_b64 v[188:189], v248 offset:32352
	ds_read_b64 v[198:199], v248 offset:34624
	ds_read_b64 v[200:201], v248 offset:34656
	v_mfma_f32_16x16x32_bf16 v[66:69], v[218:221], v[182:185], v[66:69]
	ds_read_b64 v[182:183], v248 offset:30016
	ds_read_b64 v[184:185], v248 offset:30048
	v_mfma_f32_16x16x32_bf16 v[190:193], v[222:225], v[42:45], v[6:9]
	s_waitcnt lgkmcnt(8)
	v_mfma_f32_16x16x32_bf16 v[194:197], v[174:177], v[42:45], v[6:9]
	v_mfma_f32_16x16x32_bf16 v[222:225], v[222:225], v[46:49], v[14:17]
	s_nop 4
	v_exp_f32_e32 v190, v190
	s_nop 0
	v_exp_f32_e32 v194, v194
	v_exp_f32_e32 v191, v191
	v_mfma_f32_16x16x32_bf16 v[174:177], v[174:177], v[46:49], v[14:17]
	v_exp_f32_e32 v195, v195
	v_exp_f32_e32 v192, v192
	v_exp_f32_e32 v193, v193
	v_mfma_f32_16x16x32_bf16 v[126:129], v[240:243], v[170:173], v[126:129]
	v_exp_f32_e32 v196, v196
	v_exp_f32_e32 v197, v197
	v_cvt_pk_bf16_f32 v190, v190, v191
	v_mfma_f32_16x16x32_bf16 v[86:89], v[240:243], v[166:169], v[86:89]
	v_cvt_pk_bf16_f32 v191, v192, v193
	v_cvt_pk_bf16_f32 v192, v194, v195
	v_exp_f32_e32 v194, v222
	s_waitcnt lgkmcnt(6)
	v_mfma_f32_16x16x32_bf16 v[122:125], v[178:181], v[170:173], v[122:125]
	v_exp_f32_e32 v174, v174
	v_exp_f32_e32 v195, v223
	v_cvt_pk_bf16_f32 v193, v196, v197
	v_mfma_f32_16x16x32_bf16 v[78:81], v[178:181], v[166:169], v[78:81]
	s_waitcnt lgkmcnt(0)
	v_mfma_f32_16x16x32_bf16 v[118:121], v[182:185], v[170:173], v[118:121]
	v_mfma_f32_16x16x32_bf16 v[74:77], v[182:185], v[166:169], v[74:77]
	v_mfma_f32_16x16x32_bf16 v[110:113], v[186:189], v[170:173], v[110:113]
	v_mfma_f32_16x16x32_bf16 v[70:73], v[186:189], v[166:169], v[70:73]
	v_mfma_f32_16x16x32_bf16 v[106:109], v[198:201], v[170:173], v[106:109]
	v_exp_f32_e32 v170, v175
	v_exp_f32_e32 v171, v224
	v_exp_f32_e32 v172, v176
	v_mfma_f32_16x16x32_bf16 v[62:65], v[198:201], v[166:169], v[62:65]
	v_exp_f32_e32 v167, v225
	v_exp_f32_e32 v169, v177
	v_cvt_pk_bf16_f32 v166, v194, v195
	v_cvt_pk_bf16_f32 v168, v174, v170
	v_cvt_pk_bf16_f32 v167, v171, v167
	v_cvt_pk_bf16_f32 v169, v172, v169
	v_mfma_f32_16x16x32_bf16 v[114:117], v[240:243], v[190:193], v[114:117]
	s_nop 0
	v_mfma_f32_16x16x32_bf16 v[82:85], v[240:243], v[166:169], v[82:85]
	v_mfma_f32_16x16x32_bf16 v[102:105], v[178:181], v[190:193], v[102:105]
	v_mfma_f32_16x16x32_bf16 v[58:61], v[178:181], v[166:169], v[58:61]
	v_mfma_f32_16x16x32_bf16 v[98:101], v[182:185], v[190:193], v[98:101]
	v_mfma_f32_16x16x32_bf16 v[54:57], v[182:185], v[166:169], v[54:57]
	v_mfma_f32_16x16x32_bf16 v[94:97], v[186:189], v[190:193], v[94:97]
	v_mfma_f32_16x16x32_bf16 v[50:53], v[186:189], v[166:169], v[50:53]
	v_mfma_f32_16x16x32_bf16 v[90:93], v[198:201], v[190:193], v[90:93]
	v_mfma_f32_16x16x32_bf16 v[66:69], v[198:201], v[166:169], v[66:69]
	s_cbranch_vccnz .LBB0_2162
.LBB0_2160:
	s_and_b32 s0, s10, 0x80
	s_lshl_b32 s1, s0, 7
	s_add_i32 s37, s1, 0
	s_lshl_b32 s0, s0, 4
	s_add_i32 s2, s37, s0
	s_cmpk_gt_u32 s36, 0x101
	s_cselect_b64 s[0:1], -1, 0
	s_and_b64 vcc, exec, s[0:1]
	s_waitcnt vmcnt(3)
	ds_write_b128 v244, v[18:21]
	s_waitcnt vmcnt(1)
	ds_write_b128 v245, v[22:25] offset:0
	s_waitcnt vmcnt(1)
	ds_write_b128 v244, v[26:29] offset:8192
	s_waitcnt vmcnt(0)
	ds_write_b128 v245, v[30:33] offset:9216
	s_waitcnt lgkmcnt(0)
	s_barrier
	ds_read_b128 v[130:133], v246
	ds_read_b128 v[166:169], v246 offset:2048
	s_cbranch_vccnz .LBB0_2159
	s_cmp_eq_u32 s10, 0
	s_cbranch_scc0 .Lpf_next_2159
	v_add_u32_e32 v250, s34, v159
	v_mad_i64_i32 v[250:251], s[38:39], v250, s19, v[144:145]
	v_add_u32_e32 v252, s35, v159
	v_mad_i64_i32 v[252:253], s[38:39], v252, s19, v[144:145]
	s_sub_i32 s100, s33, s34
	s_mul_hi_i32 s101, s100, 0x1640
	s_mul_i32 s100, s100, 0x1640
	s_branch .Lpf_load_2159
